# v10 + RG-LRU gate math: -log2e pre-scale of every exp argument folded into fmamk / pre-scaled softplus constant (192 fewer VALU per loop trip pair)
# baseline (speedup 1.0000x reference)
.LBB0_709:
	v_add_u32_e32 v80, s11, v114
	v_add_u32_e32 v118, 16, v80
	v_add_u32_e32 v32, 0x210, v80
	v_ashrrev_i32_e32 v119, 31, v118
	v_ashrrev_i32_e32 v33, 31, v32
	v_lshlrev_b64 v[16:17], 7, v[118:119]
	v_lshlrev_b64 v[24:25], 7, v[32:33]
	v_lshlrev_b64 v[34:35], 2, v[118:119]
	v_add_u32_e32 v94, 0x410, v80
	v_add_u32_e32 v96, 0x610, v80
	v_lshl_add_u64 v[20:21], v[112:113], 0, v[16:17]
	v_lshl_add_u64 v[28:29], v[112:113], 0, v[24:25]
	v_lshl_add_u64 v[36:37], s[38:39], 0, v[34:35]
	v_lshl_add_u64 v[32:33], v[32:33], 2, s[38:39]
	v_ashrrev_i32_e32 v95, 31, v94
	v_ashrrev_i32_e32 v97, 31, v96
	global_load_dwordx4 v[16:19], v[20:21], off
	s_nop 0
	global_load_dwordx4 v[20:23], v[20:21], off offset:64
	s_nop 0
	global_load_dwordx4 v[24:27], v[28:29], off
	s_nop 0
	global_load_dwordx4 v[28:31], v[28:29], off offset:64
	v_lshlrev_b64 v[40:41], 7, v[96:97]
	global_load_dword v131, v[36:37], off
	global_load_dword v132, v[32:33], off
	v_lshlrev_b64 v[32:33], 7, v[94:95]
	v_lshl_add_u64 v[86:87], s[48:49], 0, v[34:35]
	v_lshl_add_u64 v[36:37], v[112:113], 0, v[32:33]
	v_lshl_add_u64 v[44:45], v[112:113], 0, v[40:41]
	v_lshl_add_u64 v[94:95], v[94:95], 2, s[38:39]
	global_load_dword v133, v[86:87], off
	global_load_dwordx4 v[32:35], v[36:37], off
	s_nop 0
	global_load_dwordx4 v[36:39], v[36:37], off offset:64
	s_nop 0
	global_load_dwordx4 v[40:43], v[44:45], off
	s_nop 0
	global_load_dwordx4 v[44:47], v[44:45], off offset:64
	s_waitcnt vmcnt(24) lgkmcnt(3)
	v_mfma_f32_16x16x32_bf16 v[100:103], v[0:3], v[64:67], 0
	global_load_dword v134, v[94:95], off
	v_lshl_add_u64 v[94:95], v[96:97], 2, s[38:39]
	global_load_dword v135, v[94:95], off
	global_load_dword v136, v[86:87], off offset:2048
	s_waitcnt lgkmcnt(1)
	v_mfma_f32_16x16x32_bf16 v[104:107], v[8:11], v[64:67], 0
	ds_read_u16 v85, v130
	ds_read_u16 v86, v130 offset:1024
	ds_read_u16 v88, v130 offset:2048
	ds_read_u16 v90, v130 offset:3072
	ds_read_u16 v93, v130 offset:4096
	ds_read_u16 v94, v130 offset:5120
	ds_read_u16 v95, v130 offset:6144
	ds_read_u16 v99, v130 offset:19456
	s_waitcnt lgkmcnt(8)
	ds_bpermute_b32 v81, v115, v121
	ds_bpermute_b32 v87, v115, v120
	ds_bpermute_b32 v96, v115, v122
	ds_bpermute_b32 v97, v115, v123
	s_waitcnt vmcnt(26)
	v_mfma_f32_16x16x32_bf16 v[64:67], v[4:7], v[72:75], v[100:103]
	ds_bpermute_b32 v98, v115, v124
	s_waitcnt lgkmcnt(12)
	v_lshlrev_b32_e32 v85, 16, v85
	s_waitcnt lgkmcnt(11)
	v_lshlrev_b32_e32 v86, 16, v86
	s_waitcnt vmcnt(25)
	v_mfma_f32_16x16x32_bf16 v[100:103], v[0:3], v[68:71], 0
	s_waitcnt lgkmcnt(3)
	v_fma_f32 v85, v81, v85, v87
	v_lshlrev_b32_e32 v88, 16, v88
	s_waitcnt lgkmcnt(2)
	v_fmac_f32_e32 v85, v96, v86
	v_mfma_f32_16x16x32_bf16 v[72:75], v[12:15], v[72:75], v[104:107]
	v_fma_f32 v86, v81, v86, v87
	v_lshlrev_b32_e32 v90, 16, v90
	s_waitcnt lgkmcnt(1)
	v_fmac_f32_e32 v85, v97, v88
	v_mfma_f32_16x16x32_bf16 v[104:107], v[8:11], v[68:71], 0
	v_fmac_f32_e32 v86, v96, v88
	v_fma_f32 v88, v81, v88, v87
	v_lshlrev_b32_e32 v93, 16, v93
	s_waitcnt vmcnt(24)
	v_mfma_f32_16x16x32_bf16 v[68:71], v[4:7], v[76:79], v[100:103]
	s_waitcnt lgkmcnt(0)
	v_fmac_f32_e32 v85, v98, v90
	v_fmac_f32_e32 v86, v97, v90
	v_fmac_f32_e32 v88, v96, v90
	s_waitcnt vmcnt(15)
	v_mfma_f32_16x16x32_bf16 v[100:103], v[0:3], v[48:51], 0
	v_fma_f32 v90, v81, v90, v87
	v_lshlrev_b32_e32 v94, 16, v94
	v_fmac_f32_e32 v86, v98, v93
	v_mfma_f32_16x16x32_bf16 v[76:79], v[12:15], v[76:79], v[104:107]
	v_fmac_f32_e32 v88, v97, v93
	v_fmac_f32_e32 v90, v96, v93
	ds_read_u16 v93, v130 offset:16384
	v_mfma_f32_16x16x32_bf16 v[104:107], v[8:11], v[48:51], 0
	v_lshlrev_b32_e32 v95, 16, v95
	v_fmac_f32_e32 v88, v98, v94
	v_fmac_f32_e32 v90, v97, v94
	v_mfma_f32_16x16x32_bf16 v[48:51], v[4:7], v[56:59], v[100:103]
	ds_read_u16 v94, v130 offset:17408
	v_fmac_f32_e32 v90, v98, v95
	ds_read_u16 v95, v130 offset:18432
	v_mfma_f32_16x16x32_bf16 v[100:103], v[0:3], v[52:55], 0
	v_mul_f32_e32 v92, 0xbfb8aa3b, v92
	v_mul_f32_e32 v91, 0xbfb8aa3b, v91
	v_fmamk_f32 v72, v72, 0xbfb8aa3b, v92
	v_fmamk_f32 v76, v76, 0xbfb8aa3b, v91
	v_exp_f32_e32 v72, v72
	v_exp_f32_e32 v76, v76
	v_mfma_f32_16x16x32_bf16 v[56:59], v[12:15], v[56:59], v[104:107]
	v_lshlrev_b32_e32 v99, 16, v99
	v_add_f32_e32 v72, 1.0, v72
	v_add_f32_e32 v76, 1.0, v76
	v_mfma_f32_16x16x32_bf16 v[104:107], v[8:11], v[52:55], 0
	v_fmamk_f32 v64, v64, 0xbfb8aa3b, v92
	v_mfma_f32_16x16x32_bf16 v[52:55], v[4:7], v[60:63], v[100:103]
	v_fmamk_f32 v68, v68, 0xbfb8aa3b, v91
	v_exp_f32_e32 v64, v64
	v_exp_f32_e32 v68, v68
	ds_read_u16 v100, v130 offset:20480
	ds_read_u16 v101, v130 offset:21504
	ds_read_u16 v102, v130 offset:22528
	s_waitcnt lgkmcnt(5)
	v_lshlrev_b32_e32 v93, 16, v93
	s_waitcnt lgkmcnt(4)
	v_lshlrev_b32_e32 v94, 16, v94
	v_fma_f32 v93, v81, v93, v87
	s_waitcnt lgkmcnt(3)
	v_lshlrev_b32_e32 v95, 16, v95
	v_fmac_f32_e32 v93, v96, v94
	v_fma_f32 v94, v81, v94, v87
	v_fmac_f32_e32 v93, v97, v95
	v_fmac_f32_e32 v94, v96, v95
	v_fma_f32 v95, v81, v95, v87
	v_fmac_f32_e32 v93, v98, v99
	v_fmac_f32_e32 v94, v97, v99
	v_fmac_f32_e32 v95, v96, v99
	v_fmac_f32_e32 v87, v81, v99
	v_mul_f32_e32 v99, v72, v76
	v_rcp_f32_e32 v99, v99
	v_fmamk_f32 v65, v65, 0xbfb8aa3b, v92
	v_mul_f32_e32 v76, v76, v99
	v_mul_f32_e32 v89, 0xbfb8aa3b, v89
	v_mul_f32_e32 v76, v76, v89
	v_exp_f32_e32 v76, v76
	v_fmamk_f32 v69, v69, 0xbfb8aa3b, v91
	v_exp_f32_e32 v65, v65
	v_exp_f32_e32 v69, v69
	v_fmamk_f32 v66, v66, 0xbfb8aa3b, v92
	v_fmamk_f32 v70, v70, 0xbfb8aa3b, v91
	v_add_f32_e32 v64, 1.0, v64
	v_add_f32_e32 v68, 1.0, v68
	v_fmamk_f32 v75, v75, 0xbfb8aa3b, v92
	v_fmamk_f32 v79, v79, 0xbfb8aa3b, v91
	v_fmamk_f32 v74, v74, 0xbfb8aa3b, v92
	v_fmamk_f32 v78, v78, 0xbfb8aa3b, v91
	v_fmamk_f32 v73, v73, 0xbfb8aa3b, v92
	v_fmamk_f32 v77, v77, 0xbfb8aa3b, v91
	v_mul_f32_e32 v72, v72, v99
	v_fma_f32 v99, -v76, v76, 1.0
	v_fmamk_f32 v67, v67, 0xbfb8aa3b, v92
	v_fmamk_f32 v71, v71, 0xbfb8aa3b, v91
	v_exp_f32_e32 v66, v66
	v_exp_f32_e32 v70, v70
	v_mul_f32_e32 v91, v64, v68
	s_waitcnt lgkmcnt(2)
	v_lshlrev_b32_e32 v100, 16, v100
	v_exp_f32_e32 v75, v75
	v_exp_f32_e32 v79, v79
	v_exp_f32_e32 v74, v74
	v_exp_f32_e32 v78, v78
	v_exp_f32_e32 v73, v73
	v_exp_f32_e32 v77, v77
	v_max_f32_e32 v99, 0, v99
	v_exp_f32_e32 v67, v67
	v_exp_f32_e32 v71, v71
	v_rcp_f32_e32 v91, v91
	s_waitcnt lgkmcnt(1)
	v_lshlrev_b32_e32 v101, 16, v101
	v_fmac_f32_e32 v95, v97, v100
	v_fmac_f32_e32 v87, v96, v100
	v_sqrt_f32_e32 v99, v99
	v_add_f32_e32 v65, 1.0, v65
	v_add_f32_e32 v69, 1.0, v69
	v_fmac_f32_e32 v95, v98, v101
	v_fmac_f32_e32 v87, v97, v101
	v_mul_f32_e32 v101, v65, v69
	v_add_f32_e32 v66, 1.0, v66
	v_add_f32_e32 v70, 1.0, v70
	v_rcp_f32_e32 v101, v101
	s_waitcnt lgkmcnt(0)
	v_lshlrev_b32_e32 v102, 16, v102
	v_fmac_f32_e32 v94, v98, v100
	v_add_f32_e32 v75, 1.0, v75
	v_add_f32_e32 v79, 1.0, v79
	v_add_f32_e32 v74, 1.0, v74
	v_add_f32_e32 v78, 1.0, v78
	v_add_f32_e32 v73, 1.0, v73
	v_add_f32_e32 v77, 1.0, v77
	v_mul_f32_e32 v72, v72, v93
	v_add_f32_e32 v67, 1.0, v67
	v_add_f32_e32 v71, 1.0, v71
	v_mul_f32_e32 v100, v66, v70
	v_mul_f32_e32 v68, v68, v91
	v_fmac_f32_e32 v87, v98, v102
	v_mul_f32_e32 v96, v75, v79
	v_mul_f32_e32 v97, v74, v78
	v_mul_f32_e32 v98, v73, v77
	v_mul_f32_e32 v72, v99, v72
	v_mul_f32_e32 v99, v67, v71
	v_rcp_f32_e32 v100, v100
	v_mul_f32_e32 v68, v68, v89
	v_rcp_f32_e32 v96, v96
	v_rcp_f32_e32 v97, v97
	v_rcp_f32_e32 v98, v98
	v_rcp_f32_e32 v99, v99
	v_mul_f32_e32 v69, v69, v101
	v_exp_f32_e32 v68, v68
	v_mul_f32_e32 v69, v69, v89
	v_mul_f32_e32 v70, v70, v100
	v_mul_f32_e32 v79, v79, v96
	v_mul_f32_e32 v78, v78, v97
	v_mul_f32_e32 v77, v77, v98
	v_mul_f32_e32 v71, v71, v99
	v_mul_f32_e32 v70, v70, v89
	v_exp_f32_e32 v69, v69
	v_mul_f32_e32 v79, v79, v89
	v_mul_f32_e32 v78, v78, v89
	v_mul_f32_e32 v77, v77, v89
	v_mul_f32_e32 v71, v71, v89
	v_fma_f32 v89, -v68, v68, 1.0
	v_exp_f32_e32 v70, v70
	v_max_f32_e32 v89, 0, v89
	v_sqrt_f32_e32 v89, v89
	v_exp_f32_e32 v71, v71
	v_mul_f32_e32 v65, v65, v101
	v_fma_f32 v101, -v69, v69, 1.0
	v_max_f32_e32 v101, 0, v101
	v_mul_f32_e32 v64, v64, v91
	v_mul_f32_e32 v66, v66, v100
	v_fma_f32 v100, -v70, v70, 1.0
	v_sqrt_f32_e32 v101, v101
	v_mul_f32_e32 v64, v64, v85
	v_max_f32_e32 v100, 0, v100
	v_mul_f32_e32 v64, v89, v64
	v_mul_f32_e32 v67, v67, v99
	v_fma_f32 v99, -v71, v71, 1.0
	v_sqrt_f32_e32 v100, v100
	v_fmac_f32_e32 v64, 0, v68
	v_max_f32_e32 v99, 0, v99
	v_mul_f32_e32 v65, v65, v86
	v_mul_f32_e32 v64, v69, v64
	v_sqrt_f32_e32 v99, v99
	v_fmac_f32_e32 v64, v101, v65
	v_mul_f32_e32 v66, v66, v88
	v_mul_f32_e32 v64, v70, v64
	v_mul_f32_e32 v65, v68, v69
	v_fmac_f32_e32 v64, v100, v66
	v_mul_f32_e32 v67, v67, v90
	v_mul_f32_e32 v65, v70, v65
	v_mul_f32_e32 v64, v71, v64
	v_fmac_f32_e32 v64, v99, v67
	v_mul_f32_e32 v65, v71, v65
	ds_bpermute_b32 v66, v128, v65
	ds_bpermute_b32 v67, v128, v64
	v_exp_f32_e32 v77, v77
	s_waitcnt lgkmcnt(1)
	v_mul_f32_e32 v66, v65, v66
	s_waitcnt lgkmcnt(0)
	v_fma_f32 v67, v65, v67, v64
	v_exp_f32_e32 v78, v78
	v_cndmask_b32_e64 v64, v67, v64, s[44:45]
	v_cndmask_b32_e64 v65, v66, v65, s[44:45]
	ds_bpermute_b32 v66, v126, v65
	ds_bpermute_b32 v67, v126, v64
	v_exp_f32_e32 v79, v79
	v_mul_f32_e32 v73, v73, v98
	v_fma_f32 v98, -v77, v77, 1.0
	v_max_f32_e32 v98, 0, v98
	v_mul_f32_e32 v74, v74, v97
	v_fma_f32 v97, -v78, v78, 1.0
	v_sqrt_f32_e32 v98, v98
	v_max_f32_e32 v97, 0, v97
	v_mul_f32_e32 v75, v75, v96
	v_fma_f32 v96, -v79, v79, 1.0
	v_sqrt_f32_e32 v97, v97
	s_waitcnt lgkmcnt(0)
	v_fma_f32 v67, v65, v67, v64
	v_mul_f32_e32 v66, v65, v66
	v_fmac_f32_e32 v72, 0, v76
	v_max_f32_e32 v96, 0, v96
	v_mul_f32_e32 v73, v73, v94
	v_cndmask_b32_e64 v67, v64, v67, s[46:47]
	v_cndmask_b32_e64 v64, v65, v66, s[46:47]
	v_mul_f32_e32 v65, v77, v72
	v_sqrt_f32_e32 v96, v96
	v_fmac_f32_e32 v65, v98, v73
	v_mul_f32_e32 v74, v74, v95
	v_mul_f32_e32 v65, v78, v65
	ds_bpermute_b32 v66, v129, v67
	v_mul_f32_e32 v67, v76, v77
	v_fmac_f32_e32 v65, v97, v74
	v_mul_f32_e32 v75, v75, v87
	v_mul_f32_e32 v67, v78, v67
	v_mul_f32_e32 v65, v79, v65
	v_fmac_f32_e32 v65, v96, v75
	v_mul_f32_e32 v67, v79, v67
	ds_bpermute_b32 v68, v128, v67
	ds_bpermute_b32 v69, v128, v65
	ds_bpermute_b32 v64, v129, v64
	v_mfma_f32_16x16x32_bf16 v[60:63], v[12:15], v[60:63], v[104:107]
	v_ashrrev_i32_e32 v81, 31, v80
	s_waitcnt lgkmcnt(2)
	v_mul_f32_e32 v68, v67, v68
	s_waitcnt lgkmcnt(1)
	v_fma_f32 v69, v67, v69, v65
	v_cndmask_b32_e64 v65, v69, v65, s[44:45]
	v_cndmask_b32_e64 v67, v68, v67, s[44:45]
	ds_bpermute_b32 v68, v126, v67
	ds_bpermute_b32 v69, v126, v65
	s_waitcnt lgkmcnt(1)
	v_mul_f32_e32 v68, v67, v68
	s_waitcnt lgkmcnt(0)
	v_fma_f32 v69, v67, v69, v65
	v_cndmask_b32_e64 v65, v65, v69, s[46:47]
	v_cndmask_b32_e64 v67, v67, v68, s[46:47]
	ds_bpermute_b32 v67, v129, v67
	ds_bpermute_b32 v65, v129, v65
	s_and_saveexec_b64 s[4:5], s[44:45]
	s_cbranch_execz .LBB0_711
	s_waitcnt lgkmcnt(0)
	v_fmac_f32_e32 v65, v66, v67
	v_mul_f32_e32 v64, v64, v67
	v_lshl_add_u64 v[66:67], v[80:81], 3, s[58:59]
	global_store_dwordx2 v[66:67], v[64:65], off
.LBB0_711:
	s_or_b64 exec, exec, s[4:5]
	v_mul_f32_e32 v84, 0xbfb8aa3b, v84
	v_mul_f32_e32 v83, 0xbfb8aa3b, v83
	v_fmamk_f32 v51, v51, 0xbfb8aa3b, v84
	v_fmamk_f32 v55, v55, 0xbfb8aa3b, v83
	v_exp_f32_e32 v51, v51
	v_exp_f32_e32 v55, v55
	v_add_f32_e32 v51, 1.0, v51
	v_add_f32_e32 v55, 1.0, v55
	s_waitcnt lgkmcnt(1)
	v_mul_f32_e32 v67, v51, v55
	v_rcp_f32_e32 v67, v67
	v_fmamk_f32 v50, v50, 0xbfb8aa3b, v84
	v_fmamk_f32 v54, v54, 0xbfb8aa3b, v83
	v_exp_f32_e32 v50, v50
	v_mul_f32_e32 v55, v55, v67
	s_waitcnt vmcnt(14)
	v_mul_f32_e32 v82, 0xbfb8aa3b, v82
	v_mul_f32_e32 v55, v55, v82
	v_exp_f32_e32 v55, v55
	v_mul_f32_e32 v51, v51, v67
	v_exp_f32_e32 v54, v54
	v_mul_f32_e32 v51, v51, v90
	v_fma_f32 v67, -v55, v55, 1.0
	v_max_f32_e32 v67, 0, v67
	v_sqrt_f32_e32 v67, v67
	v_add_f32_e32 v50, 1.0, v50
	v_add_f32_e32 v54, 1.0, v54
	v_mul_f32_e32 v51, v51, v67
	v_mul_f32_e32 v67, v50, v54
	v_rcp_f32_e32 v67, v67
	v_fmamk_f32 v49, v49, 0xbfb8aa3b, v84
	v_mul_f32_e32 v50, v50, v67
	v_mul_f32_e32 v68, v50, v88
	v_mul_f32_e32 v50, v54, v67
	v_mul_f32_e32 v50, v50, v82
	v_exp_f32_e32 v54, v50
	v_exp_f32_e32 v49, v49
	v_fmamk_f32 v59, v59, 0xbfb8aa3b, v84
	v_fmamk_f32 v63, v63, 0xbfb8aa3b, v83
	v_fma_f32 v50, -v54, v54, 1.0
	v_max_f32_e32 v50, 0, v50
	v_sqrt_f32_e32 v67, v50
	v_fmamk_f32 v50, v53, 0xbfb8aa3b, v83
	v_exp_f32_e32 v50, v50
	v_exp_f32_e32 v59, v59
	v_exp_f32_e32 v63, v63
	v_add_f32_e32 v49, 1.0, v49
	v_add_f32_e32 v50, 1.0, v50
	v_mul_f32_e32 v53, v49, v50
	v_add_f32_e32 v59, 1.0, v59
	v_add_f32_e32 v63, 1.0, v63
	v_rcp_f32_e32 v53, v53
	v_mul_f32_e32 v64, v59, v63
	v_rcp_f32_e32 v64, v64
	v_mul_f32_e32 v50, v50, v53
	v_mul_f32_e32 v50, v50, v82
	v_mul_f32_e32 v59, v59, v64
	s_waitcnt lgkmcnt(0)
	v_mul_f32_e32 v65, v59, v87
	v_mul_f32_e32 v59, v63, v64
	v_mul_f32_e32 v49, v49, v53
	v_exp_f32_e32 v53, v50
	v_mul_f32_e32 v59, v59, v82
	v_exp_f32_e32 v59, v59
	v_fma_f32 v50, -v53, v53, 1.0
	v_fmamk_f32 v58, v58, 0xbfb8aa3b, v84
	v_fmamk_f32 v62, v62, 0xbfb8aa3b, v83
	v_max_f32_e32 v50, 0, v50
	v_exp_f32_e32 v58, v58
	v_exp_f32_e32 v62, v62
	v_sqrt_f32_e32 v69, v50
	v_fma_f32 v63, -v59, v59, 1.0
	v_fmamk_f32 v57, v57, 0xbfb8aa3b, v84
	v_fmamk_f32 v61, v61, 0xbfb8aa3b, v83
	v_fmamk_f32 v48, v48, 0xbfb8aa3b, v84
	v_fmamk_f32 v50, v52, 0xbfb8aa3b, v83
	v_max_f32_e32 v63, 0, v63
	v_exp_f32_e32 v57, v57
	v_exp_f32_e32 v61, v61
	v_exp_f32_e32 v48, v48
	v_exp_f32_e32 v50, v50
	v_sqrt_f32_e32 v63, v63
	v_fmamk_f32 v56, v56, 0xbfb8aa3b, v84
	v_fmamk_f32 v60, v60, 0xbfb8aa3b, v83
	v_add_f32_e32 v58, 1.0, v58
	v_add_f32_e32 v62, 1.0, v62
	v_exp_f32_e32 v56, v56
	v_exp_f32_e32 v60, v60
	v_mul_f32_e32 v64, v58, v62
	v_rcp_f32_e32 v64, v64
	v_add_f32_e32 v57, 1.0, v57
	v_add_f32_e32 v61, 1.0, v61
	v_add_f32_e32 v48, 1.0, v48
	v_add_f32_e32 v50, 1.0, v50
	v_mul_f32_e32 v63, v63, v65
	v_mul_f32_e32 v65, v57, v61
	v_mul_f32_e32 v52, v48, v50
	v_rcp_f32_e32 v65, v65
	v_add_f32_e32 v56, 1.0, v56
	v_add_f32_e32 v60, 1.0, v60
	v_rcp_f32_e32 v52, v52
	v_mul_f32_e32 v66, v56, v60
	v_mul_f32_e32 v62, v62, v64
	v_rcp_f32_e32 v66, v66
	v_mul_f32_e32 v62, v62, v82
	v_mul_f32_e32 v61, v61, v65
	v_mul_f32_e32 v48, v48, v52
	v_exp_f32_e32 v62, v62
	v_mul_f32_e32 v61, v61, v82
	v_mul_f32_e32 v70, v48, v85
	v_mul_f32_e32 v48, v50, v52
	v_mul_f32_e32 v60, v60, v66
	v_mul_f32_e32 v48, v48, v82
	v_exp_f32_e32 v61, v61
	v_mul_f32_e32 v60, v60, v82
	v_exp_f32_e32 v52, v48
	v_mul_f32_e32 v58, v58, v64
	v_fma_f32 v64, -v62, v62, 1.0
	v_exp_f32_e32 v60, v60
	v_max_f32_e32 v64, 0, v64
	v_sqrt_f32_e32 v64, v64
	v_mul_f32_e32 v57, v57, v65
	v_fma_f32 v65, -v61, v61, 1.0
	v_max_f32_e32 v65, 0, v65
	v_fma_f32 v48, -v52, v52, 1.0
	v_sqrt_f32_e32 v65, v65
	v_mul_f32_e32 v56, v56, v66
	v_fma_f32 v66, -v60, v60, 1.0
	v_max_f32_e32 v48, 0, v48
	v_fmac_f32_e32 v63, 0, v59
	v_fmac_f32_e32 v51, 0, v55
	v_mul_f32_e32 v58, v58, v95
	v_max_f32_e32 v66, 0, v66
	v_sqrt_f32_e32 v71, v48
	v_mul_f32_e32 v48, v62, v63
	v_mul_f32_e32 v51, v54, v51
	v_sqrt_f32_e32 v66, v66
	v_fmac_f32_e32 v48, v64, v58
	v_fmac_f32_e32 v51, v68, v67
	v_mul_f32_e32 v57, v57, v94
	v_mul_f32_e32 v49, v49, v86
	v_mul_f32_e32 v48, v61, v48
	v_mul_f32_e32 v51, v53, v51
	v_mul_f32_e32 v50, v59, v62
	v_fmac_f32_e32 v48, v65, v57
	v_mul_f32_e32 v54, v55, v54
	v_fmac_f32_e32 v51, v49, v69
	v_mul_f32_e32 v56, v56, v93
	v_mul_f32_e32 v50, v61, v50
	v_mul_f32_e32 v48, v60, v48
	v_mul_f32_e32 v49, v53, v54
	v_mul_f32_e32 v51, v52, v51
	v_fmac_f32_e32 v48, v66, v56
	v_mul_f32_e32 v50, v60, v50
	v_fmac_f32_e32 v51, v70, v71
	v_mul_f32_e32 v49, v52, v49
	ds_bpermute_b32 v56, v125, v50
	ds_bpermute_b32 v57, v125, v48
	ds_bpermute_b32 v52, v125, v49
	ds_bpermute_b32 v53, v125, v51
	s_waitcnt lgkmcnt(3)
	v_mul_f32_e32 v56, v50, v56
	s_waitcnt lgkmcnt(2)
	v_fma_f32 v57, v50, v57, v48
	s_waitcnt lgkmcnt(1)
	v_mul_f32_e32 v52, v49, v52
	s_waitcnt lgkmcnt(0)
	v_fma_f32 v53, v49, v53, v51
	v_cndmask_b32_e64 v48, v57, v48, s[40:41]
	v_cndmask_b32_e64 v50, v56, v50, s[40:41]
	v_cndmask_b32_e64 v51, v53, v51, s[40:41]
	v_cndmask_b32_e64 v49, v52, v49, s[40:41]
	ds_bpermute_b32 v56, v126, v50
	ds_bpermute_b32 v57, v126, v48
	ds_bpermute_b32 v52, v126, v49
	ds_bpermute_b32 v53, v126, v51
	s_waitcnt lgkmcnt(3)
	v_mul_f32_e32 v56, v50, v56
	s_waitcnt lgkmcnt(2)
	v_fma_f32 v57, v50, v57, v48
	s_waitcnt lgkmcnt(1)
	v_mul_f32_e32 v52, v49, v52
	s_waitcnt lgkmcnt(0)
	v_fma_f32 v53, v49, v53, v51
	v_cndmask_b32_e64 v57, v48, v57, s[42:43]
	v_cndmask_b32_e64 v48, v50, v56, s[42:43]
	v_cndmask_b32_e64 v53, v51, v53, s[42:43]
	v_cndmask_b32_e64 v49, v49, v52, s[42:43]
	ds_bpermute_b32 v48, v127, v48
	ds_bpermute_b32 v50, v127, v57
	ds_bpermute_b32 v51, v127, v49
	ds_bpermute_b32 v49, v127, v53
	s_and_saveexec_b64 s[4:5], s[44:45]
	s_cbranch_execz .LBB0_713
	v_lshl_add_u64 v[52:53], v[80:81], 3, s[60:61]
	s_waitcnt lgkmcnt(0)
	v_fmac_f32_e32 v49, v50, v51
	v_mul_f32_e32 v48, v48, v51
	global_store_dwordx2 v[52:53], v[48:49], off

.LBB0_715:
	ds_read_u16 v143, v130 offset:32
	ds_read_u16 v144, v130 offset:1056
	ds_read_u16 v145, v130 offset:2080
	ds_read_u16 v146, v130 offset:3104
	ds_read_u16 v148, v130 offset:4128
	ds_read_u16 v149, v130 offset:5152
	ds_read_u16 v150, v130 offset:6176
	ds_read_u16 v155, v130 offset:19488
	ds_bpermute_b32 v151, v115, v121 offset:64
	ds_bpermute_b32 v147, v115, v120 offset:64
	ds_bpermute_b32 v152, v115, v122 offset:64
	v_mfma_f32_16x16x32_bf16 v[84:87], v[8:11], v[16:19], 0
	ds_bpermute_b32 v153, v115, v123 offset:64
	ds_bpermute_b32 v154, v115, v124 offset:64
	s_waitcnt lgkmcnt(12)
	v_lshlrev_b32_e32 v143, 16, v143
	v_mfma_f32_16x16x32_bf16 v[104:107], v[12:15], v[20:23], v[84:87]
	s_waitcnt lgkmcnt(11)
	v_lshlrev_b32_e32 v144, 16, v144
	s_waitcnt lgkmcnt(3)
	v_fma_f32 v143, v151, v143, v147
	v_lshlrev_b32_e32 v145, 16, v145
	v_mfma_f32_16x16x32_bf16 v[84:87], v[8:11], v[24:27], 0
	s_waitcnt lgkmcnt(2)
	v_fmac_f32_e32 v143, v152, v144
	v_fma_f32 v144, v151, v144, v147
	v_lshlrev_b32_e32 v146, 16, v146
	s_waitcnt lgkmcnt(1)
	v_fmac_f32_e32 v143, v153, v145
	v_fmac_f32_e32 v144, v152, v145
	v_fma_f32 v145, v151, v145, v147
	v_lshlrev_b32_e32 v148, 16, v148
	s_waitcnt lgkmcnt(0)
	v_fmac_f32_e32 v143, v154, v146
	v_fmac_f32_e32 v144, v153, v146
	v_fmac_f32_e32 v145, v152, v146
	v_fma_f32 v146, v151, v146, v147
	v_mfma_f32_16x16x32_bf16 v[108:111], v[12:15], v[28:31], v[84:87]
	v_lshlrev_b32_e32 v149, 16, v149
	v_fmac_f32_e32 v144, v154, v148
	v_fmac_f32_e32 v145, v153, v148
	v_fmac_f32_e32 v146, v152, v148
	ds_read_u16 v148, v130 offset:16416
	ds_read_u16 v156, v130 offset:20512
	ds_read_u16 v157, v130 offset:21536
	ds_read_u16 v158, v130 offset:22560
	v_lshlrev_b32_e32 v150, 16, v150
	v_fmac_f32_e32 v145, v154, v149
	v_fmac_f32_e32 v146, v153, v149
	ds_read_u16 v149, v130 offset:17440
	v_fmac_f32_e32 v146, v154, v150
	ds_read_u16 v150, v130 offset:18464
	v_mfma_f32_16x16x32_bf16 v[80:83], v[0:3], v[16:19], 0
	v_mul_f32_e32 v131, 0xbfb8aa3b, v131
	v_mul_f32_e32 v132, 0xbfb8aa3b, v132
	s_waitcnt lgkmcnt(5)
	v_lshlrev_b32_e32 v148, 16, v148
	v_fmamk_f32 v104, v104, 0xbfb8aa3b, v131
	v_fmamk_f32 v108, v108, 0xbfb8aa3b, v132
	s_waitcnt lgkmcnt(1)
	v_lshlrev_b32_e32 v149, 16, v149
	v_fma_f32 v148, v151, v148, v147
	v_exp_f32_e32 v104, v104
	v_exp_f32_e32 v108, v108
	v_mfma_f32_16x16x32_bf16 v[96:99], v[4:7], v[20:23], v[80:83]
	s_waitcnt lgkmcnt(0)
	v_lshlrev_b32_e32 v150, 16, v150
	v_lshlrev_b32_e32 v155, 16, v155
	v_fmac_f32_e32 v148, v152, v149
	v_mfma_f32_16x16x32_bf16 v[80:83], v[0:3], v[24:27], 0
	v_fma_f32 v149, v151, v149, v147
	v_lshlrev_b32_e32 v156, 16, v156
	v_fmac_f32_e32 v148, v153, v150
	v_fmac_f32_e32 v149, v152, v150
	v_fma_f32 v150, v151, v150, v147
	v_fmac_f32_e32 v147, v151, v155
	v_lshlrev_b32_e32 v157, 16, v157
	v_fmac_f32_e32 v150, v152, v155
	v_fmac_f32_e32 v147, v152, v156
	v_lshlrev_b32_e32 v158, 16, v158
	v_fmac_f32_e32 v149, v153, v155
	v_fmac_f32_e32 v150, v153, v156
	v_fmac_f32_e32 v147, v153, v157
	v_add_f32_e32 v104, 1.0, v104
	v_add_f32_e32 v108, 1.0, v108
	v_mfma_f32_16x16x32_bf16 v[100:103], v[4:7], v[28:31], v[80:83]
	v_fmac_f32_e32 v148, v154, v155
	v_fmac_f32_e32 v149, v154, v156
	v_fmac_f32_e32 v150, v154, v157
	v_fmac_f32_e32 v147, v154, v158
	v_mul_f32_e32 v154, v104, v108
	v_rcp_f32_e32 v154, v154
	s_nop 0
	v_fmamk_f32 v96, v96, 0xbfb8aa3b, v131
	v_mul_f32_e32 v108, v108, v154
	v_fmamk_f32 v100, v100, 0xbfb8aa3b, v132
	v_mul_f32_e32 v133, 0xbfb8aa3b, v133
	v_mul_f32_e32 v108, v108, v133
	v_exp_f32_e32 v96, v96
	v_exp_f32_e32 v100, v100
	v_exp_f32_e32 v108, v108
	v_fmamk_f32 v97, v97, 0xbfb8aa3b, v131
	v_fmamk_f32 v101, v101, 0xbfb8aa3b, v132
	v_exp_f32_e32 v97, v97
	v_exp_f32_e32 v101, v101
	v_fmamk_f32 v98, v98, 0xbfb8aa3b, v131
	v_fmamk_f32 v102, v102, 0xbfb8aa3b, v132
	v_add_f32_e32 v96, 1.0, v96
	v_add_f32_e32 v100, 1.0, v100
	v_exp_f32_e32 v98, v98
	v_exp_f32_e32 v102, v102
	v_mul_f32_e32 v157, v96, v100
	v_mul_f32_e32 v104, v104, v154
	v_fma_f32 v154, -v108, v108, 1.0
	v_fmamk_f32 v99, v99, 0xbfb8aa3b, v131
	v_fmamk_f32 v103, v103, 0xbfb8aa3b, v132
	v_rcp_f32_e32 v157, v157
	v_max_f32_e32 v154, 0, v154
	v_exp_f32_e32 v99, v99
	v_exp_f32_e32 v103, v103
	v_add_f32_e32 v97, 1.0, v97
	v_add_f32_e32 v101, 1.0, v101
	v_sqrt_f32_e32 v154, v154
	v_mul_f32_e32 v156, v97, v101
	v_add_f32_e32 v98, 1.0, v98
	v_add_f32_e32 v102, 1.0, v102
	v_rcp_f32_e32 v156, v156
	v_mul_f32_e32 v155, v98, v102
	v_mul_f32_e32 v100, v100, v157
	v_mul_f32_e32 v104, v104, v148
	v_add_f32_e32 v99, 1.0, v99
	v_add_f32_e32 v103, 1.0, v103
	v_rcp_f32_e32 v155, v155
	v_mul_f32_e32 v100, v100, v133
	v_mul_f32_e32 v104, v154, v104
	v_mul_f32_e32 v154, v99, v103
	v_rcp_f32_e32 v154, v154
	v_mul_f32_e32 v101, v101, v156
	v_exp_f32_e32 v100, v100
	v_mul_f32_e32 v101, v101, v133
	v_mul_f32_e32 v102, v102, v155
	v_mul_f32_e32 v102, v102, v133
	v_exp_f32_e32 v101, v101
	v_mul_f32_e32 v103, v103, v154
	v_mul_f32_e32 v96, v96, v157
	v_fma_f32 v157, -v100, v100, 1.0
	v_mul_f32_e32 v103, v103, v133
	v_exp_f32_e32 v102, v102
	v_max_f32_e32 v157, 0, v157
	v_sqrt_f32_e32 v157, v157
	v_exp_f32_e32 v103, v103
	v_mul_f32_e32 v97, v97, v156
	v_fma_f32 v156, -v101, v101, 1.0
	v_fmamk_f32 v105, v105, 0xbfb8aa3b, v131
	v_fmamk_f32 v109, v109, 0xbfb8aa3b, v132
	v_max_f32_e32 v156, 0, v156
	v_exp_f32_e32 v105, v105
	v_exp_f32_e32 v109, v109
	v_mul_f32_e32 v98, v98, v155
	v_fma_f32 v155, -v102, v102, 1.0
	v_sqrt_f32_e32 v156, v156
	v_mul_f32_e32 v96, v96, v143
	v_fmamk_f32 v106, v106, 0xbfb8aa3b, v131
	v_fmamk_f32 v110, v110, 0xbfb8aa3b, v132
	v_max_f32_e32 v155, 0, v155
	v_mul_f32_e32 v96, v157, v96
	v_exp_f32_e32 v106, v106
	v_exp_f32_e32 v110, v110
	v_mul_f32_e32 v99, v99, v154
	v_fma_f32 v154, -v103, v103, 1.0
	v_sqrt_f32_e32 v155, v155
	v_fmac_f32_e32 v96, 0, v100
	v_fmamk_f32 v107, v107, 0xbfb8aa3b, v131
	v_fmamk_f32 v111, v111, 0xbfb8aa3b, v132
	v_max_f32_e32 v154, 0, v154
	v_mul_f32_e32 v97, v97, v144
	v_mul_f32_e32 v96, v101, v96
	v_exp_f32_e32 v107, v107
	v_exp_f32_e32 v111, v111
	v_add_f32_e32 v105, 1.0, v105
	v_add_f32_e32 v109, 1.0, v109
	v_sqrt_f32_e32 v154, v154
	v_fmac_f32_e32 v96, v156, v97
	v_mul_f32_e32 v153, v105, v109
	v_mul_f32_e32 v98, v98, v145
	v_mul_f32_e32 v96, v102, v96
	v_add_f32_e32 v106, 1.0, v106
	v_add_f32_e32 v110, 1.0, v110
	v_rcp_f32_e32 v153, v153
	v_mul_f32_e32 v97, v100, v101
	v_fmac_f32_e32 v96, v155, v98
	v_mul_f32_e32 v152, v106, v110
	v_mul_f32_e32 v99, v99, v146
	v_mul_f32_e32 v97, v102, v97
	v_mul_f32_e32 v96, v103, v96
	v_add_f32_e32 v107, 1.0, v107
	v_add_f32_e32 v111, 1.0, v111
	v_rcp_f32_e32 v152, v152
	v_fmac_f32_e32 v96, v154, v99
	v_mul_f32_e32 v97, v103, v97
	v_mul_f32_e32 v151, v107, v111
	ds_bpermute_b32 v98, v128, v97
	ds_bpermute_b32 v99, v128, v96
	v_rcp_f32_e32 v151, v151
	v_mul_f32_e32 v109, v109, v153
	v_mul_f32_e32 v109, v109, v133
	v_mul_f32_e32 v110, v110, v152
	v_mul_f32_e32 v110, v110, v133
	v_exp_f32_e32 v109, v109
	v_mul_f32_e32 v111, v111, v151
	s_waitcnt lgkmcnt(0)
	v_fma_f32 v99, v97, v99, v96
	v_mul_f32_e32 v98, v97, v98
	v_mul_f32_e32 v111, v111, v133
	v_exp_f32_e32 v110, v110
	v_cndmask_b32_e64 v96, v99, v96, s[44:45]
	v_cndmask_b32_e64 v97, v98, v97, s[44:45]
	ds_bpermute_b32 v98, v126, v97
	ds_bpermute_b32 v99, v126, v96
	v_exp_f32_e32 v111, v111
	v_mul_f32_e32 v105, v105, v153
	v_fma_f32 v153, -v109, v109, 1.0
	v_max_f32_e32 v153, 0, v153
	v_mul_f32_e32 v106, v106, v152
	v_fma_f32 v152, -v110, v110, 1.0
	v_sqrt_f32_e32 v153, v153
	v_max_f32_e32 v152, 0, v152
	v_mul_f32_e32 v107, v107, v151
	v_fma_f32 v151, -v111, v111, 1.0
	v_sqrt_f32_e32 v152, v152
	s_waitcnt lgkmcnt(0)
	v_fma_f32 v99, v97, v99, v96
	v_mul_f32_e32 v98, v97, v98
	v_fmac_f32_e32 v104, 0, v108
	v_max_f32_e32 v151, 0, v151
	v_mul_f32_e32 v105, v105, v149
	v_cndmask_b32_e64 v99, v96, v99, s[46:47]
	v_cndmask_b32_e64 v96, v97, v98, s[46:47]
	v_mul_f32_e32 v97, v109, v104
	v_sqrt_f32_e32 v151, v151
	v_fmac_f32_e32 v97, v153, v105
	v_mul_f32_e32 v106, v106, v150
	v_mul_f32_e32 v97, v110, v97
	ds_bpermute_b32 v98, v129, v99
	v_mul_f32_e32 v99, v108, v109
	v_fmac_f32_e32 v97, v152, v106
	v_mul_f32_e32 v107, v107, v147
	v_mul_f32_e32 v99, v110, v99
	v_mul_f32_e32 v97, v111, v97
	v_fmac_f32_e32 v97, v151, v107
	v_mul_f32_e32 v99, v111, v99
	ds_bpermute_b32 v100, v128, v99
	ds_bpermute_b32 v101, v128, v97
	v_mfma_f32_16x16x32_bf16 v[80:83], v[0:3], v[32:35], 0
	ds_bpermute_b32 v96, v129, v96
	s_waitcnt lgkmcnt(2)
	v_mul_f32_e32 v100, v99, v100
	s_waitcnt lgkmcnt(1)
	v_fma_f32 v101, v99, v101, v97
	v_cndmask_b32_e64 v97, v101, v97, s[44:45]
	v_cndmask_b32_e64 v99, v100, v99, s[44:45]
	v_mfma_f32_16x16x32_bf16 v[88:91], v[8:11], v[32:35], 0
	ds_bpermute_b32 v100, v126, v99
	ds_bpermute_b32 v101, v126, v97
	s_waitcnt lgkmcnt(1)
	v_mul_f32_e32 v100, v99, v100
	v_mfma_f32_16x16x32_bf16 v[84:87], v[4:7], v[36:39], v[80:83]
	s_waitcnt lgkmcnt(0)
	v_fma_f32 v101, v99, v101, v97
	v_cndmask_b32_e64 v97, v97, v101, s[46:47]
	v_cndmask_b32_e64 v99, v99, v100, s[46:47]
	v_mfma_f32_16x16x32_bf16 v[92:95], v[12:15], v[36:39], v[88:91]
	ds_bpermute_b32 v99, v129, v99
	ds_bpermute_b32 v97, v129, v97
	v_mfma_f32_16x16x32_bf16 v[80:83], v[0:3], v[40:43], 0
	v_mfma_f32_16x16x32_bf16 v[88:91], v[8:11], v[40:43], 0
	v_mfma_f32_16x16x32_bf16 v[80:83], v[4:7], v[44:47], v[80:83]
	v_mfma_f32_16x16x32_bf16 v[88:91], v[12:15], v[44:47], v[88:91]
	s_and_saveexec_b64 s[4:5], s[44:45]
	s_cbranch_execz .LBB0_717
	s_waitcnt lgkmcnt(0)
	v_fmac_f32_e32 v97, v98, v99
	v_mul_f32_e32 v96, v96, v99
	global_store_dwordx2 v[116:117], v[96:97], off offset:-4
.LBB0_717:
	s_or_b64 exec, exec, s[4:5]
	v_mul_f32_e32 v134, 0xbfb8aa3b, v134
	s_nop 2
	v_mul_f32_e32 v135, 0xbfb8aa3b, v135
	v_fmamk_f32 v87, v87, 0xbfb8aa3b, v134
	v_fmamk_f32 v83, v83, 0xbfb8aa3b, v135
	v_exp_f32_e32 v87, v87
	v_exp_f32_e32 v83, v83
	v_add_f32_e32 v87, 1.0, v87
	v_add_f32_e32 v83, 1.0, v83
	s_waitcnt lgkmcnt(1)
	v_mul_f32_e32 v99, v87, v83
	v_rcp_f32_e32 v99, v99
	v_fmamk_f32 v86, v86, 0xbfb8aa3b, v134
	v_fmamk_f32 v82, v82, 0xbfb8aa3b, v135
	v_exp_f32_e32 v86, v86
	v_mul_f32_e32 v83, v83, v99
	v_mul_f32_e32 v136, 0xbfb8aa3b, v136
	v_mul_f32_e32 v83, v83, v136
	v_exp_f32_e32 v83, v83
	v_mul_f32_e32 v87, v87, v99
	v_exp_f32_e32 v82, v82
	v_mul_f32_e32 v87, v87, v146
	v_fma_f32 v99, -v83, v83, 1.0
	v_max_f32_e32 v99, 0, v99
	v_sqrt_f32_e32 v99, v99
	v_add_f32_e32 v86, 1.0, v86
	v_add_f32_e32 v82, 1.0, v82
	v_mul_f32_e32 v87, v87, v99
	v_mul_f32_e32 v99, v86, v82
	v_rcp_f32_e32 v99, v99
	v_fmamk_f32 v95, v95, 0xbfb8aa3b, v134
	v_mul_f32_e32 v82, v82, v99
	v_mul_f32_e32 v82, v82, v136
	v_mul_f32_e32 v86, v86, v99
	v_exp_f32_e32 v99, v82
	v_fmamk_f32 v91, v91, 0xbfb8aa3b, v135
	v_fmamk_f32 v81, v81, 0xbfb8aa3b, v135
	v_exp_f32_e32 v95, v95
	v_fma_f32 v82, -v99, v99, 1.0
	v_max_f32_e32 v82, 0, v82
	v_sqrt_f32_e32 v100, v82
	v_fmamk_f32 v82, v85, 0xbfb8aa3b, v134
	v_exp_f32_e32 v91, v91
	v_exp_f32_e32 v82, v82
	v_exp_f32_e32 v81, v81
	v_add_f32_e32 v95, 1.0, v95
	v_add_f32_e32 v91, 1.0, v91
	v_add_f32_e32 v82, 1.0, v82
	v_add_f32_e32 v81, 1.0, v81
	v_mul_f32_e32 v96, v95, v91
	v_mul_f32_e32 v85, v82, v81
	v_rcp_f32_e32 v96, v96
	v_rcp_f32_e32 v85, v85
	v_mul_f32_e32 v91, v91, v96
	v_mul_f32_e32 v81, v81, v85
	v_mul_f32_e32 v91, v91, v136
	v_mul_f32_e32 v81, v81, v136
	v_exp_f32_e32 v91, v91
	v_exp_f32_e32 v81, v81
	v_mul_f32_e32 v82, v82, v85
	v_mul_f32_e32 v95, v95, v96
	v_fma_f32 v96, -v91, v91, 1.0
	v_fmamk_f32 v94, v94, 0xbfb8aa3b, v134
	v_fmamk_f32 v90, v90, 0xbfb8aa3b, v135
	v_mul_f32_e32 v101, v82, v144
	v_fma_f32 v82, -v81, v81, 1.0
	v_max_f32_e32 v96, 0, v96
	v_exp_f32_e32 v94, v94
	v_exp_f32_e32 v90, v90
	v_max_f32_e32 v82, 0, v82
	v_sqrt_f32_e32 v96, v96
	v_fmamk_f32 v93, v93, 0xbfb8aa3b, v134
	v_fmamk_f32 v89, v89, 0xbfb8aa3b, v135
	v_sqrt_f32_e32 v85, v82
	v_exp_f32_e32 v93, v93
	v_exp_f32_e32 v89, v89
	v_fmamk_f32 v82, v84, 0xbfb8aa3b, v134
	v_fmamk_f32 v80, v80, 0xbfb8aa3b, v135
	v_fmamk_f32 v92, v92, 0xbfb8aa3b, v134
	v_fmamk_f32 v88, v88, 0xbfb8aa3b, v135
	v_exp_f32_e32 v82, v82
	v_exp_f32_e32 v80, v80
	v_mul_f32_e32 v95, v95, v147
	v_add_f32_e32 v94, 1.0, v94
	v_add_f32_e32 v90, 1.0, v90
	v_exp_f32_e32 v92, v92
	v_exp_f32_e32 v88, v88
	v_mul_f32_e32 v95, v96, v95
	v_mul_f32_e32 v96, v94, v90
	v_rcp_f32_e32 v96, v96
	v_add_f32_e32 v93, 1.0, v93
	v_add_f32_e32 v89, 1.0, v89
	s_waitcnt lgkmcnt(0)
	v_mul_f32_e32 v97, v93, v89
	v_add_f32_e32 v82, 1.0, v82
	v_add_f32_e32 v80, 1.0, v80
	v_rcp_f32_e32 v97, v97
	v_add_f32_e32 v92, 1.0, v92
	v_add_f32_e32 v88, 1.0, v88
	v_mul_f32_e32 v84, v82, v80
	v_mul_f32_e32 v98, v92, v88
	v_rcp_f32_e32 v84, v84
	v_mul_f32_e32 v90, v90, v96
	v_rcp_f32_e32 v98, v98
	v_mul_f32_e32 v90, v90, v136
	v_mul_f32_e32 v89, v89, v97
	v_exp_f32_e32 v90, v90
	v_mul_f32_e32 v89, v89, v136
	v_mul_f32_e32 v80, v80, v84
	v_mul_f32_e32 v88, v88, v98
	v_mul_f32_e32 v80, v80, v136
	v_exp_f32_e32 v89, v89
	v_mul_f32_e32 v88, v88, v136
	v_mul_f32_e32 v82, v82, v84
	v_exp_f32_e32 v84, v80
	v_mul_f32_e32 v94, v94, v96
	v_fma_f32 v96, -v90, v90, 1.0
	v_exp_f32_e32 v88, v88
	v_max_f32_e32 v96, 0, v96
	v_sqrt_f32_e32 v96, v96
	v_mul_f32_e32 v93, v93, v97
	v_fma_f32 v97, -v89, v89, 1.0
	v_max_f32_e32 v97, 0, v97
	v_fma_f32 v80, -v84, v84, 1.0
	v_sqrt_f32_e32 v97, v97
	v_mul_f32_e32 v92, v92, v98
	v_fma_f32 v98, -v88, v88, 1.0
	v_max_f32_e32 v80, 0, v80
	v_fmac_f32_e32 v95, 0, v91
	v_fmac_f32_e32 v87, 0, v83
	v_mul_f32_e32 v94, v94, v150
	v_max_f32_e32 v98, 0, v98
	v_mul_f32_e32 v86, v86, v145
	v_sqrt_f32_e32 v103, v80
	v_mul_f32_e32 v80, v90, v95
	v_mul_f32_e32 v87, v99, v87
	v_sqrt_f32_e32 v98, v98
	v_fmac_f32_e32 v80, v96, v94
	v_fmac_f32_e32 v87, v86, v100
	v_mul_f32_e32 v93, v93, v149
	v_mul_f32_e32 v80, v89, v80
	v_mul_f32_e32 v86, v81, v87
	v_mul_f32_e32 v102, v82, v143
	v_mul_f32_e32 v82, v91, v90
	v_fmac_f32_e32 v80, v97, v93
	v_mul_f32_e32 v83, v83, v99
	v_fmac_f32_e32 v86, v101, v85
	v_mul_f32_e32 v92, v92, v148
	v_mul_f32_e32 v82, v89, v82
	v_mul_f32_e32 v80, v88, v80
	v_mul_f32_e32 v81, v81, v83
	v_mul_f32_e32 v83, v84, v86
	v_fmac_f32_e32 v80, v98, v92
	v_mul_f32_e32 v82, v88, v82
	v_fmac_f32_e32 v83, v102, v103
	v_mul_f32_e32 v81, v84, v81
	ds_bpermute_b32 v88, v125, v82
	ds_bpermute_b32 v89, v125, v80
	ds_bpermute_b32 v84, v125, v81
	ds_bpermute_b32 v85, v125, v83
	s_waitcnt lgkmcnt(3)
	v_mul_f32_e32 v88, v82, v88
	s_waitcnt lgkmcnt(2)
	v_fma_f32 v89, v82, v89, v80
	s_waitcnt lgkmcnt(1)
	v_mul_f32_e32 v84, v81, v84
	s_waitcnt lgkmcnt(0)
	v_fma_f32 v85, v81, v85, v83
	v_cndmask_b32_e64 v80, v89, v80, s[40:41]
	v_cndmask_b32_e64 v82, v88, v82, s[40:41]
	v_cndmask_b32_e64 v83, v85, v83, s[40:41]
	v_cndmask_b32_e64 v81, v84, v81, s[40:41]
	ds_bpermute_b32 v88, v126, v82
	ds_bpermute_b32 v89, v126, v80
	ds_bpermute_b32 v84, v126, v81
	ds_bpermute_b32 v85, v126, v83
	s_waitcnt lgkmcnt(3)
	v_mul_f32_e32 v88, v82, v88
	s_waitcnt lgkmcnt(2)
	v_fma_f32 v89, v82, v89, v80
	s_waitcnt lgkmcnt(1)
	v_mul_f32_e32 v84, v81, v84
	s_waitcnt lgkmcnt(0)
	v_fma_f32 v85, v81, v85, v83
	v_cndmask_b32_e64 v89, v80, v89, s[42:43]
	v_cndmask_b32_e64 v80, v82, v88, s[42:43]
	v_cndmask_b32_e64 v85, v83, v85, s[42:43]
	v_cndmask_b32_e64 v81, v81, v84, s[42:43]
	ds_bpermute_b32 v80, v127, v80
	ds_bpermute_b32 v82, v127, v89
	ds_bpermute_b32 v83, v127, v81
	ds_bpermute_b32 v81, v127, v85
	s_and_saveexec_b64 s[4:5], s[44:45]
	s_cbranch_execz .LBB0_719
	v_lshl_add_u64 v[84:85], v[118:119], 3, s[60:61]
	s_waitcnt lgkmcnt(0)
	v_fmac_f32_e32 v81, v82, v83
	v_mul_f32_e32 v80, v80, v83
	global_store_dwordx2 v[84:85], v[80:81], off

.LBB0_821:
	s_waitcnt vmcnt(13)
	v_mfma_f32_16x16x32_bf16 v[102:105], v[0:3], v[64:67], 0
	v_add_u32_e32 v82, s26, v126
	v_add_u32_e32 v32, 16, v82
	v_add_u32_e32 v34, 0x210, v82
	v_mfma_f32_16x16x32_bf16 v[106:109], v[8:11], v[64:67], 0
	v_ashrrev_i32_e32 v33, 31, v32
	v_ashrrev_i32_e32 v35, 31, v34
	v_add_u32_e32 v84, 0x410, v82
	s_waitcnt vmcnt(12)
	v_mfma_f32_16x16x32_bf16 v[64:67], v[4:7], v[72:75], v[102:105]
	v_add_u32_e32 v90, 0x610, v82
	v_lshlrev_b64 v[16:17], 7, v[32:33]
	v_lshlrev_b64 v[24:25], 7, v[34:35]
	s_waitcnt vmcnt(11)
	v_mfma_f32_16x16x32_bf16 v[102:105], v[0:3], v[68:71], 0
	v_lshlrev_b64 v[32:33], 2, v[32:33]
	v_ashrrev_i32_e32 v85, 31, v84
	v_ashrrev_i32_e32 v91, 31, v90
	v_lshl_add_u64 v[20:21], v[116:117], 0, v[16:17]
	v_lshl_add_u64 v[28:29], v[116:117], 0, v[24:25]
	v_lshl_add_u64 v[36:37], s[38:39], 0, v[32:33]
	v_lshl_add_u64 v[34:35], v[34:35], 2, s[38:39]
	v_lshl_add_u64 v[80:81], s[0:1], 0, v[32:33]
	v_lshlrev_b64 v[32:33], 7, v[84:85]
	v_lshlrev_b64 v[40:41], 7, v[90:91]
	v_mfma_f32_16x16x32_bf16 v[72:75], v[12:15], v[72:75], v[106:109]
	global_load_dwordx4 v[16:19], v[20:21], off
	s_nop 0
	global_load_dwordx4 v[20:23], v[20:21], off offset:64
	s_nop 0
	global_load_dwordx4 v[24:27], v[28:29], off
	s_nop 0
	global_load_dwordx4 v[28:31], v[28:29], off offset:64
	v_lshl_add_u64 v[44:45], v[116:117], 0, v[40:41]
	v_mfma_f32_16x16x32_bf16 v[106:109], v[8:11], v[68:71], 0
	global_load_dword v134, v[36:37], off
	global_load_dword v135, v[34:35], off
	v_lshl_add_u64 v[36:37], v[116:117], 0, v[32:33]
	s_waitcnt vmcnt(16)
	v_mfma_f32_16x16x32_bf16 v[68:71], v[4:7], v[76:79], v[102:105]
	v_lshl_add_u64 v[84:85], v[84:85], 2, s[38:39]
	global_load_dword v136, v[80:81], off
	global_load_dwordx4 v[32:35], v[36:37], off
	s_nop 0
	global_load_dwordx4 v[36:39], v[36:37], off offset:64
	s_waitcnt vmcnt(10)
	v_mfma_f32_16x16x32_bf16 v[102:105], v[0:3], v[48:51], 0
	global_load_dwordx4 v[40:43], v[44:45], off
	s_nop 0
	global_load_dwordx4 v[44:47], v[44:45], off offset:64
	v_add_u32_e32 v140, s35, v133
	global_load_dword v137, v[84:85], off
	v_lshl_add_u64 v[84:85], v[90:91], 2, s[38:39]
	global_load_dword v138, v[84:85], off
	global_load_dword v139, v[80:81], off offset:2048
	v_lshl_add_u64 v[80:81], v[172:173], 0, s[70:71]
	ds_read_u16 v90, v140
	ds_read_u16 v91, v140 offset:1024
	ds_read_u16 v93, v140 offset:2048
	ds_read_u16 v97, v140 offset:3072
	ds_read_u16 v98, v140 offset:4096
	ds_read_u16 v99, v140 offset:5120
	ds_read_u16 v100, v140 offset:6144
	ds_bpermute_b32 v83, v80, v122
	ds_bpermute_b32 v92, v80, v114
	v_mfma_f32_16x16x32_bf16 v[76:79], v[12:15], v[76:79], v[106:109]
	ds_bpermute_b32 v84, v80, v123
	ds_bpermute_b32 v85, v80, v124
	ds_bpermute_b32 v101, v80, v125
	v_mfma_f32_16x16x32_bf16 v[106:109], v[8:11], v[48:51], 0
	v_mul_f32_e32 v96, 0xbfb8aa3b, v96
	s_nop 2
	v_mul_f32_e32 v95, 0xbfb8aa3b, v95
	v_fmamk_f32 v75, v75, 0xbfb8aa3b, v96
	v_mfma_f32_16x16x32_bf16 v[48:51], v[4:7], v[56:59], v[102:105]
	v_fmamk_f32 v79, v79, 0xbfb8aa3b, v95
	v_exp_f32_e32 v75, v75
	v_exp_f32_e32 v79, v79
	v_mfma_f32_16x16x32_bf16 v[102:105], v[0:3], v[52:55], 0
	v_add_f32_e32 v75, 1.0, v75
	v_add_f32_e32 v79, 1.0, v79
	v_mfma_f32_16x16x32_bf16 v[56:59], v[12:15], v[56:59], v[106:109]
	v_fmamk_f32 v74, v74, 0xbfb8aa3b, v96
	v_fmamk_f32 v78, v78, 0xbfb8aa3b, v95
	v_mfma_f32_16x16x32_bf16 v[106:109], v[8:11], v[52:55], 0
	v_exp_f32_e32 v74, v74
	v_exp_f32_e32 v78, v78
	v_mfma_f32_16x16x32_bf16 v[52:55], v[4:7], v[60:63], v[102:105]
	v_add_f32_e32 v74, 1.0, v74
	v_add_f32_e32 v78, 1.0, v78
	ds_read_u16 v102, v140 offset:19456
	s_waitcnt lgkmcnt(12)
	v_lshlrev_b32_e32 v90, 16, v90
	s_waitcnt lgkmcnt(11)
	v_lshlrev_b32_e32 v91, 16, v91
	s_waitcnt lgkmcnt(4)
	v_fma_f32 v90, v83, v90, v92
	v_lshlrev_b32_e32 v93, 16, v93
	s_waitcnt lgkmcnt(3)
	v_fmac_f32_e32 v90, v84, v91
	v_fma_f32 v91, v83, v91, v92
	v_lshlrev_b32_e32 v97, 16, v97
	s_waitcnt lgkmcnt(2)
	v_fmac_f32_e32 v90, v85, v93
	v_fmac_f32_e32 v91, v84, v93
	v_fma_f32 v93, v83, v93, v92
	v_lshlrev_b32_e32 v98, 16, v98
	s_waitcnt lgkmcnt(1)
	v_fmac_f32_e32 v90, v101, v97
	v_fmac_f32_e32 v91, v85, v97
	v_fmac_f32_e32 v93, v84, v97
	v_fma_f32 v97, v83, v97, v92
	v_lshlrev_b32_e32 v99, 16, v99
	v_fmac_f32_e32 v91, v101, v98
	v_fmac_f32_e32 v93, v85, v98
	v_fmac_f32_e32 v97, v84, v98
	ds_read_u16 v98, v140 offset:16384
	ds_read_u16 v103, v140 offset:20480
	ds_read_u16 v104, v140 offset:21504
	ds_read_u16 v105, v140 offset:22528
	v_lshlrev_b32_e32 v100, 16, v100
	v_fmac_f32_e32 v93, v101, v99
	v_fmac_f32_e32 v97, v85, v99
	ds_read_u16 v99, v140 offset:17408
	v_fmac_f32_e32 v97, v101, v100
	ds_read_u16 v100, v140 offset:18432
	s_waitcnt lgkmcnt(5)
	v_lshlrev_b32_e32 v98, 16, v98
	v_fma_f32 v98, v83, v98, v92
	s_waitcnt lgkmcnt(1)
	v_lshlrev_b32_e32 v99, 16, v99
	v_lshlrev_b32_e32 v102, 16, v102
	s_waitcnt lgkmcnt(0)
	v_lshlrev_b32_e32 v100, 16, v100
	v_fmac_f32_e32 v98, v84, v99
	v_fma_f32 v99, v83, v99, v92
	v_lshlrev_b32_e32 v103, 16, v103
	v_fmac_f32_e32 v98, v85, v100
	v_fmac_f32_e32 v99, v84, v100
	v_fma_f32 v100, v83, v100, v92
	v_fmac_f32_e32 v92, v83, v102
	v_lshlrev_b32_e32 v104, 16, v104
	v_fmac_f32_e32 v100, v84, v102
	v_fmac_f32_e32 v92, v84, v103
	v_ashrrev_i32_e32 v83, 31, v82
	v_fmac_f32_e32 v99, v85, v102
	v_fmac_f32_e32 v100, v85, v103
	v_fmac_f32_e32 v92, v85, v104
	v_lshl_add_u64 v[84:85], v[82:83], 2, s[48:49]
	v_mul_f32_e32 v83, v75, v79
	v_rcp_f32_e32 v83, v83
	v_lshlrev_b32_e32 v105, 16, v105
	v_fmac_f32_e32 v92, v101, v105
	v_fmamk_f32 v73, v73, 0xbfb8aa3b, v96
	v_mul_f32_e32 v79, v79, v83
	v_mul_f32_e32 v94, 0xbfb8aa3b, v94
	v_mul_f32_e32 v79, v79, v94
	v_exp_f32_e32 v79, v79
	v_mul_f32_e32 v75, v75, v83
	v_mul_f32_e32 v75, v75, v92
	v_fmamk_f32 v77, v77, 0xbfb8aa3b, v95
	v_fma_f32 v83, -v79, v79, 1.0
	v_max_f32_e32 v83, 0, v83
	v_sqrt_f32_e32 v83, v83
	v_exp_f32_e32 v73, v73
	v_exp_f32_e32 v77, v77
	v_fmac_f32_e32 v100, v101, v104
	v_mul_f32_e32 v75, v83, v75
	v_mul_f32_e32 v83, v74, v78
	v_rcp_f32_e32 v83, v83
	v_add_f32_e32 v73, 1.0, v73
	v_add_f32_e32 v77, 1.0, v77
	v_mul_f32_e32 v78, v78, v83
	v_mul_f32_e32 v78, v78, v94
	v_exp_f32_e32 v78, v78
	v_mul_f32_e32 v74, v74, v83
	v_mul_f32_e32 v74, v74, v100
	v_fma_f32 v83, -v78, v78, 1.0
	v_max_f32_e32 v83, 0, v83
	v_sqrt_f32_e32 v83, v83
	v_fmamk_f32 v72, v72, 0xbfb8aa3b, v96
	v_fmamk_f32 v76, v76, 0xbfb8aa3b, v95
	v_exp_f32_e32 v72, v72
	v_mul_f32_e32 v74, v83, v74
	v_mul_f32_e32 v83, v73, v77
	v_rcp_f32_e32 v83, v83
	v_exp_f32_e32 v76, v76
	v_fmac_f32_e32 v99, v101, v103
	v_add_f32_e32 v72, 1.0, v72
	v_mul_f32_e32 v77, v77, v83
	v_mul_f32_e32 v77, v77, v94
	v_mul_f32_e32 v73, v73, v83
	v_exp_f32_e32 v83, v77
	v_mul_f32_e32 v73, v73, v99
	v_add_f32_e32 v76, 1.0, v76
	v_fmac_f32_e32 v98, v101, v102
	v_fma_f32 v77, -v83, v83, 1.0
	v_max_f32_e32 v77, 0, v77
	v_sqrt_f32_e32 v77, v77
	v_fmamk_f32 v67, v67, 0xbfb8aa3b, v96
	v_mul_f32_e32 v73, v77, v73
	v_mul_f32_e32 v77, v72, v76
	v_rcp_f32_e32 v77, v77
	v_fmamk_f32 v71, v71, 0xbfb8aa3b, v95
	v_exp_f32_e32 v67, v67
	v_exp_f32_e32 v71, v71
	v_mul_f32_e32 v76, v76, v77
	v_mul_f32_e32 v76, v76, v94
	v_exp_f32_e32 v101, v76
	v_mul_f32_e32 v72, v72, v77
	v_mul_f32_e32 v72, v72, v98
	v_add_f32_e32 v67, 1.0, v67
	v_fma_f32 v76, -v101, v101, 1.0
	v_max_f32_e32 v76, 0, v76
	v_sqrt_f32_e32 v76, v76
	v_add_f32_e32 v71, 1.0, v71
	v_mul_f32_e32 v72, v76, v72
	v_mul_f32_e32 v76, v67, v71
	v_rcp_f32_e32 v76, v76
	v_fmamk_f32 v66, v66, 0xbfb8aa3b, v96
	v_fmamk_f32 v70, v70, 0xbfb8aa3b, v95
	v_exp_f32_e32 v66, v66
	v_mul_f32_e32 v67, v67, v76
	v_mul_f32_e32 v77, v67, v97
	v_mul_f32_e32 v67, v71, v76
	v_mul_f32_e32 v67, v67, v94
	v_exp_f32_e32 v70, v70
	v_exp_f32_e32 v67, v67
	v_add_f32_e32 v66, 1.0, v66
	v_add_f32_e32 v70, 1.0, v70
	v_fma_f32 v71, -v67, v67, 1.0
	v_mul_f32_e32 v76, v66, v70
	v_fmamk_f32 v65, v65, 0xbfb8aa3b, v96
	v_fmamk_f32 v69, v69, 0xbfb8aa3b, v95
	v_max_f32_e32 v71, 0, v71
	v_rcp_f32_e32 v76, v76
	v_exp_f32_e32 v65, v65
	v_exp_f32_e32 v69, v69
	v_sqrt_f32_e32 v71, v71
	v_mul_f32_e32 v66, v66, v76
	v_add_f32_e32 v65, 1.0, v65
	v_add_f32_e32 v69, 1.0, v69
	v_mul_f32_e32 v71, v71, v77
	v_mul_f32_e32 v77, v66, v93
	v_mul_f32_e32 v66, v70, v76
	v_mul_f32_e32 v76, v65, v69
	v_rcp_f32_e32 v76, v76
	v_mul_f32_e32 v66, v66, v94
	v_mul_f32_e32 v69, v69, v76
	v_mul_f32_e32 v69, v69, v94
	v_exp_f32_e32 v69, v69
	v_mul_f32_e32 v65, v65, v76
	v_fmamk_f32 v64, v64, 0xbfb8aa3b, v96
	v_fmamk_f32 v68, v68, 0xbfb8aa3b, v95
	v_fma_f32 v76, -v69, v69, 1.0
	v_max_f32_e32 v76, 0, v76
	v_exp_f32_e32 v64, v64
	v_exp_f32_e32 v68, v68
	v_exp_f32_e32 v66, v66
	v_sqrt_f32_e32 v76, v76
	v_mul_f32_e32 v65, v65, v91
	v_add_f32_e32 v64, 1.0, v64
	v_add_f32_e32 v68, 1.0, v68
	v_fma_f32 v70, -v66, v66, 1.0
	v_mul_f32_e32 v65, v76, v65
	v_mul_f32_e32 v76, v64, v68
	v_max_f32_e32 v70, 0, v70
	v_rcp_f32_e32 v76, v76
	v_sqrt_f32_e32 v70, v70
	ds_bpermute_b32 v81, v80, v113
	ds_bpermute_b32 v86, v80, v115
	v_mul_f32_e32 v64, v64, v76
	v_mul_f32_e32 v70, v70, v77
	v_mul_f32_e32 v77, v64, v90
	v_mul_f32_e32 v64, v68, v76
	v_mul_f32_e32 v64, v64, v94
	v_exp_f32_e32 v64, v64
	v_mfma_f32_16x16x32_bf16 v[60:63], v[12:15], v[60:63], v[106:109]
	v_fma_f32 v68, -v64, v64, 1.0
	v_max_f32_e32 v68, 0, v68
	v_sqrt_f32_e32 v68, v68
	s_nop 0
	v_mul_f32_e32 v68, v68, v77
	v_fma_f32 v76, 0, v64, v68
	v_fma_f32 v76, v69, v76, v65
	v_mul_f32_e32 v77, v64, v69
	v_fma_f32 v76, v66, v76, v70
	v_mul_f32_e32 v77, v66, v77
	v_fma_f32 v76, v67, v76, v71
	v_mul_f32_e32 v77, v67, v77
	ds_bpermute_b32 v94, v131, v77
	ds_bpermute_b32 v95, v131, v76
	s_waitcnt lgkmcnt(1)
	v_mul_f32_e32 v94, v77, v94
	s_waitcnt lgkmcnt(0)
	v_fma_f32 v95, v77, v95, v76
	v_cndmask_b32_e64 v76, v95, v76, s[44:45]
	v_cndmask_b32_e64 v77, v94, v77, s[44:45]
	ds_bpermute_b32 v94, v129, v77
	ds_bpermute_b32 v95, v129, v76
	s_waitcnt lgkmcnt(1)
	v_mul_f32_e32 v94, v77, v94
	s_waitcnt lgkmcnt(0)
	v_fma_f32 v95, v77, v95, v76
	v_cndmask_b32_e64 v95, v76, v95, s[46:47]
	v_cndmask_b32_e64 v76, v77, v94, s[46:47]
	ds_bpermute_b32 v94, v132, v76
	ds_bpermute_b32 v96, v132, v95
	ds_bpermute_b32 v77, v131, v95
	v_mul_f32_e32 v95, v101, v83
	v_mul_f32_e32 v95, v78, v95
	v_mul_f32_e32 v95, v79, v95
	s_waitcnt lgkmcnt(1)
	v_fmac_f32_e32 v96, v81, v94
	v_fma_f32 v94, 0, v101, v72
	v_fma_f32 v94, v83, v94, v73
	v_fma_f32 v94, v78, v94, v74
	v_fma_f32 v94, v79, v94, v75
	ds_bpermute_b32 v102, v131, v95
	ds_bpermute_b32 v103, v131, v94
	ds_bpermute_b32 v76, v131, v76
	s_waitcnt lgkmcnt(2)
	v_mul_f32_e32 v102, v95, v102
	s_waitcnt lgkmcnt(1)
	v_fma_f32 v103, v95, v103, v94
	v_cndmask_b32_e64 v94, v103, v94, s[44:45]
	v_cndmask_b32_e64 v95, v102, v95, s[44:45]
	ds_bpermute_b32 v102, v129, v95
	ds_bpermute_b32 v103, v129, v94
	s_waitcnt lgkmcnt(1)
	v_mul_f32_e32 v102, v95, v102
	s_waitcnt lgkmcnt(0)
	v_fma_f32 v103, v95, v103, v94
	v_cndmask_b32_e64 v94, v94, v103, s[46:47]
	v_cndmask_b32_e64 v95, v95, v102, s[46:47]
	ds_bpermute_b32 v95, v131, v95
	ds_bpermute_b32 v94, v131, v94
	s_waitcnt lgkmcnt(1)
	v_cndmask_b32_e64 v95, v95, 1.0, s[44:45]
	s_waitcnt lgkmcnt(0)
	v_cndmask_b32_e64 v94, v94, 0, s[44:45]
	v_fmac_f32_e32 v94, v96, v95
	v_fmac_f32_e32 v72, v101, v94
	v_fmac_f32_e32 v73, v83, v72
	v_fmac_f32_e32 v74, v78, v73
	v_fmac_f32_e32 v75, v79, v74
	s_and_saveexec_b64 s[4:5], s[68:69]
	s_cbranch_execz .LBB0_823
	global_store_dword v[84:85], v75, off
.LBB0_823:
	s_or_b64 exec, exec, s[4:5]
	v_mul_f32_e32 v89, 0xbfb8aa3b, v89
	v_mul_f32_e32 v88, 0xbfb8aa3b, v88
	v_fmamk_f32 v59, v59, 0xbfb8aa3b, v89
	v_fmamk_f32 v63, v63, 0xbfb8aa3b, v88
	v_exp_f32_e32 v59, v59
	v_exp_f32_e32 v63, v63
	v_add_f32_e32 v59, 1.0, v59
	v_add_f32_e32 v63, 1.0, v63
	v_mul_f32_e32 v78, v59, v63
	v_rcp_f32_e32 v78, v78
	v_fmamk_f32 v58, v58, 0xbfb8aa3b, v89
	v_fmamk_f32 v62, v62, 0xbfb8aa3b, v88
	v_exp_f32_e32 v58, v58
	v_mul_f32_e32 v63, v63, v78
	s_waitcnt vmcnt(14)
	v_mul_f32_e32 v87, 0xbfb8aa3b, v87
	v_mul_f32_e32 v63, v63, v87
	v_exp_f32_e32 v63, v63
	v_mul_f32_e32 v59, v59, v78
	v_exp_f32_e32 v62, v62
	v_mul_f32_e32 v59, v59, v92
	v_fma_f32 v78, -v63, v63, 1.0
	v_max_f32_e32 v78, 0, v78
	v_sqrt_f32_e32 v78, v78
	v_add_f32_e32 v58, 1.0, v58
	v_add_f32_e32 v62, 1.0, v62
	v_mul_f32_e32 v59, v78, v59
	v_mul_f32_e32 v78, v58, v62
	v_rcp_f32_e32 v78, v78
	v_fmamk_f32 v57, v57, 0xbfb8aa3b, v89
	v_fmamk_f32 v61, v61, 0xbfb8aa3b, v88
	v_mul_f32_e32 v62, v62, v78
	v_mul_f32_e32 v62, v62, v87
	v_exp_f32_e32 v62, v62
	v_mul_f32_e32 v58, v58, v78
	v_exp_f32_e32 v57, v57
	v_exp_f32_e32 v61, v61
	v_fma_f32 v78, -v62, v62, 1.0
	v_max_f32_e32 v78, 0, v78
	v_sqrt_f32_e32 v78, v78
	v_mul_f32_e32 v58, v58, v100
	v_add_f32_e32 v57, 1.0, v57
	v_add_f32_e32 v61, 1.0, v61
	v_mul_f32_e32 v58, v78, v58
	v_mul_f32_e32 v78, v57, v61
	v_rcp_f32_e32 v78, v78
	v_fmamk_f32 v56, v56, 0xbfb8aa3b, v89
	v_mul_f32_e32 v61, v61, v78
	v_mul_f32_e32 v61, v61, v87
	v_exp_f32_e32 v61, v61
	v_mul_f32_e32 v57, v57, v78
	v_fmamk_f32 v60, v60, 0xbfb8aa3b, v88
	v_exp_f32_e32 v56, v56
	v_fma_f32 v78, -v61, v61, 1.0
	v_max_f32_e32 v78, 0, v78
	v_exp_f32_e32 v60, v60
	v_sqrt_f32_e32 v78, v78
	v_mul_f32_e32 v57, v57, v99
	v_add_f32_e32 v56, 1.0, v56
	v_add_f32_e32 v60, 1.0, v60
	v_mul_f32_e32 v57, v78, v57
	v_mul_f32_e32 v78, v56, v60
	v_rcp_f32_e32 v78, v78
	v_fmamk_f32 v51, v51, 0xbfb8aa3b, v89
	v_mul_f32_e32 v60, v60, v78
	v_mul_f32_e32 v60, v60, v87
	v_exp_f32_e32 v60, v60
	v_mul_f32_e32 v56, v56, v78
	v_fmamk_f32 v55, v55, 0xbfb8aa3b, v88
	v_exp_f32_e32 v51, v51
	v_fma_f32 v78, -v60, v60, 1.0
	v_max_f32_e32 v78, 0, v78
	v_exp_f32_e32 v55, v55
	v_sqrt_f32_e32 v78, v78
	v_mul_f32_e32 v56, v56, v98
	v_add_f32_e32 v51, 1.0, v51
	v_add_f32_e32 v55, 1.0, v55
	v_mul_f32_e32 v56, v78, v56
	v_mul_f32_e32 v78, v51, v55
	v_rcp_f32_e32 v78, v78
	v_fmamk_f32 v50, v50, 0xbfb8aa3b, v89
	v_mul_f32_e32 v55, v55, v78
	v_mul_f32_e32 v55, v55, v87
	v_exp_f32_e32 v55, v55
	v_mul_f32_e32 v51, v51, v78
	v_fmamk_f32 v54, v54, 0xbfb8aa3b, v88
	v_exp_f32_e32 v50, v50
	v_fma_f32 v78, -v55, v55, 1.0
	v_max_f32_e32 v78, 0, v78
	v_exp_f32_e32 v54, v54
	v_sqrt_f32_e32 v78, v78
	v_mul_f32_e32 v51, v51, v97
	v_add_f32_e32 v50, 1.0, v50
	v_add_f32_e32 v54, 1.0, v54
	v_mul_f32_e32 v51, v51, v78
	v_mul_f32_e32 v78, v50, v54
	v_rcp_f32_e32 v78, v78
	v_fmamk_f32 v49, v49, 0xbfb8aa3b, v89
	v_mul_f32_e32 v54, v54, v78
	v_mul_f32_e32 v54, v54, v87
	v_exp_f32_e32 v54, v54
	v_mul_f32_e32 v50, v50, v78
	v_fmamk_f32 v53, v53, 0xbfb8aa3b, v88
	v_exp_f32_e32 v49, v49
	v_fma_f32 v78, -v54, v54, 1.0
	v_max_f32_e32 v78, 0, v78
	v_exp_f32_e32 v53, v53
	v_sqrt_f32_e32 v78, v78
	v_mul_f32_e32 v50, v50, v93
	v_add_f32_e32 v49, 1.0, v49
	v_add_f32_e32 v53, 1.0, v53
	v_mul_f32_e32 v50, v50, v78
	v_mul_f32_e32 v78, v49, v53
	v_rcp_f32_e32 v78, v78
	v_fmamk_f32 v48, v48, 0xbfb8aa3b, v89
	v_mul_f32_e32 v53, v53, v78
	v_mul_f32_e32 v53, v53, v87
	v_mul_f32_e32 v49, v49, v78
	v_exp_f32_e32 v78, v53
	v_fmamk_f32 v52, v52, 0xbfb8aa3b, v88
	v_exp_f32_e32 v48, v48
	v_exp_f32_e32 v52, v52
	v_fma_f32 v53, -v78, v78, 1.0
	v_max_f32_e32 v53, 0, v53
	v_sqrt_f32_e32 v53, v53
	v_mul_f32_e32 v49, v49, v91
	v_add_f32_e32 v48, 1.0, v48
	v_add_f32_e32 v52, 1.0, v52
	v_mul_f32_e32 v49, v49, v53
	v_mul_f32_e32 v53, v48, v52
	v_rcp_f32_e32 v53, v53
	s_nop 0
	v_mul_f32_e32 v52, v52, v53
	v_mul_f32_e32 v52, v52, v87
	v_exp_f32_e32 v79, v52
	v_mul_f32_e32 v48, v48, v53
	v_mul_f32_e32 v48, v48, v90
	v_mul_f32_e32 v53, v63, v62
	v_fma_f32 v52, -v79, v79, 1.0
	v_max_f32_e32 v52, 0, v52
	v_sqrt_f32_e32 v52, v52
	v_mul_f32_e32 v53, v61, v53
	v_mul_f32_e32 v53, v60, v53
	ds_bpermute_b32 v83, v128, v53
	v_mul_f32_e32 v48, v48, v52
	v_fma_f32 v52, 0, v63, v59
	v_fma_f32 v52, v62, v52, v58
	v_fma_f32 v52, v61, v52, v57
	v_fma_f32 v52, v60, v52, v56
	ds_bpermute_b32 v87, v128, v52
	s_waitcnt lgkmcnt(1)
	v_mul_f32_e32 v83, v53, v83
	s_waitcnt lgkmcnt(0)
	v_fma_f32 v87, v53, v87, v52
	v_cndmask_b32_e64 v52, v87, v52, s[40:41]
	v_cndmask_b32_e64 v53, v83, v53, s[40:41]
	ds_bpermute_b32 v83, v129, v53
	ds_bpermute_b32 v87, v129, v52
	s_waitcnt lgkmcnt(1)
	v_mul_f32_e32 v83, v53, v83
	s_waitcnt lgkmcnt(0)
	v_fma_f32 v87, v53, v87, v52
	v_cndmask_b32_e64 v87, v52, v87, s[42:43]
	v_cndmask_b32_e64 v52, v53, v83, s[42:43]
	ds_bpermute_b32 v83, v130, v52
	ds_bpermute_b32 v88, v130, v87
	ds_bpermute_b32 v53, v128, v87
	v_mul_f32_e32 v87, v55, v54
	v_mul_f32_e32 v87, v78, v87
	v_mul_f32_e32 v87, v79, v87
	s_waitcnt lgkmcnt(1)
	v_fmac_f32_e32 v88, v86, v83
	v_fma_f32 v83, 0, v55, v51
	v_fma_f32 v83, v54, v83, v50
	v_fma_f32 v83, v78, v83, v49
	v_fma_f32 v83, v79, v83, v48
	ds_bpermute_b32 v89, v128, v87
	ds_bpermute_b32 v90, v128, v83
	ds_bpermute_b32 v52, v128, v52
	s_waitcnt lgkmcnt(2)
	v_mul_f32_e32 v89, v87, v89
	s_waitcnt lgkmcnt(1)
	v_fma_f32 v90, v87, v90, v83
	v_cndmask_b32_e64 v83, v90, v83, s[40:41]
	v_cndmask_b32_e64 v87, v89, v87, s[40:41]
	ds_bpermute_b32 v89, v129, v87
	ds_bpermute_b32 v90, v129, v83
	s_waitcnt lgkmcnt(1)
	v_mul_f32_e32 v89, v87, v89
	s_waitcnt lgkmcnt(0)
	v_fma_f32 v90, v87, v90, v83
	v_cndmask_b32_e64 v83, v83, v90, s[42:43]
	v_cndmask_b32_e64 v87, v87, v89, s[42:43]
	ds_bpermute_b32 v87, v128, v87
	ds_bpermute_b32 v83, v128, v83
	s_waitcnt lgkmcnt(1)
	v_cndmask_b32_e64 v87, v87, 1.0, s[40:41]
	s_waitcnt lgkmcnt(0)
	v_cndmask_b32_e64 v83, v83, 0, s[40:41]
	v_fmac_f32_e32 v83, v88, v87
	v_fmac_f32_e32 v51, v55, v83
	v_fmac_f32_e32 v50, v54, v51
	v_fmac_f32_e32 v49, v78, v50
	v_fmac_f32_e32 v48, v79, v49
	s_and_saveexec_b64 s[4:5], s[66:67]
	s_cbranch_execz .LBB0_825
	global_store_dword v[84:85], v48, off offset:2048

.LBB0_827:
	ds_read_u16 v149, v140 offset:32
	ds_read_u16 v150, v140 offset:1056
	ds_read_u16 v151, v140 offset:2080
	ds_read_u16 v152, v140 offset:3104
	ds_read_u16 v154, v140 offset:4128
	ds_read_u16 v155, v140 offset:5152
	ds_read_u16 v156, v140 offset:6176
	ds_read_u16 v159, v140 offset:19488
	ds_bpermute_b32 v120, v80, v122 offset:64
	ds_bpermute_b32 v153, v80, v114 offset:64
	v_mfma_f32_16x16x32_bf16 v[84:87], v[8:11], v[16:19], 0
	ds_bpermute_b32 v121, v80, v123 offset:64
	ds_bpermute_b32 v157, v80, v124 offset:64
	ds_bpermute_b32 v158, v80, v125 offset:64
	v_mfma_f32_16x16x32_bf16 v[104:107], v[12:15], v[20:23], v[84:87]
	s_waitcnt lgkmcnt(12)
	v_lshlrev_b32_e32 v149, 16, v149
	s_waitcnt lgkmcnt(11)
	v_lshlrev_b32_e32 v150, 16, v150
	s_waitcnt lgkmcnt(3)
	v_fma_f32 v149, v120, v149, v153
	v_mfma_f32_16x16x32_bf16 v[84:87], v[8:11], v[24:27], 0
	v_lshlrev_b32_e32 v151, 16, v151
	s_waitcnt lgkmcnt(2)
	v_fmac_f32_e32 v149, v121, v150
	v_fma_f32 v150, v120, v150, v153
	v_lshlrev_b32_e32 v152, 16, v152
	s_waitcnt lgkmcnt(1)
	v_fmac_f32_e32 v149, v157, v151
	v_fmac_f32_e32 v150, v121, v151
	v_fma_f32 v151, v120, v151, v153
	v_mfma_f32_16x16x32_bf16 v[108:111], v[12:15], v[28:31], v[84:87]
	v_lshlrev_b32_e32 v154, 16, v154
	s_waitcnt lgkmcnt(0)
	v_fmac_f32_e32 v149, v158, v152
	v_fmac_f32_e32 v150, v157, v152
	v_fmac_f32_e32 v151, v121, v152
	v_fma_f32 v152, v120, v152, v153
	v_lshlrev_b32_e32 v155, 16, v155
	v_fmac_f32_e32 v150, v158, v154
	v_fmac_f32_e32 v151, v157, v154
	v_fmac_f32_e32 v152, v121, v154
	ds_read_u16 v154, v140 offset:16416
	ds_read_u16 v160, v140 offset:20512
	ds_read_u16 v161, v140 offset:21536
	ds_read_u16 v162, v140 offset:22560
	v_lshlrev_b32_e32 v156, 16, v156
	v_fmac_f32_e32 v151, v158, v155
	v_fmac_f32_e32 v152, v157, v155
	ds_read_u16 v155, v140 offset:17440
	v_fmac_f32_e32 v152, v158, v156
	ds_read_u16 v156, v140 offset:18464
	v_mul_f32_e32 v134, 0xbfb8aa3b, v134
	v_mul_f32_e32 v135, 0xbfb8aa3b, v135
	v_fmamk_f32 v107, v107, 0xbfb8aa3b, v134
	v_fmamk_f32 v111, v111, 0xbfb8aa3b, v135
	s_waitcnt lgkmcnt(5)
	v_lshlrev_b32_e32 v154, 16, v154
	v_exp_f32_e32 v107, v107
	v_exp_f32_e32 v111, v111
	s_waitcnt lgkmcnt(1)
	v_lshlrev_b32_e32 v155, 16, v155
	v_fma_f32 v154, v120, v154, v153
	s_waitcnt lgkmcnt(0)
	v_lshlrev_b32_e32 v156, 16, v156
	v_lshlrev_b32_e32 v159, 16, v159
	v_fmac_f32_e32 v154, v121, v155
	v_fma_f32 v155, v120, v155, v153
	v_lshlrev_b32_e32 v160, 16, v160
	v_fmac_f32_e32 v154, v157, v156
	v_fmac_f32_e32 v155, v121, v156
	v_fma_f32 v156, v120, v156, v153
	v_fmac_f32_e32 v153, v120, v159
	v_lshlrev_b32_e32 v161, 16, v161
	v_fmac_f32_e32 v156, v121, v159
	v_fmac_f32_e32 v153, v121, v160
	v_add_f32_e32 v107, 1.0, v107
	v_add_f32_e32 v111, 1.0, v111
	v_fmac_f32_e32 v155, v157, v159
	v_fmac_f32_e32 v156, v157, v160
	v_fmac_f32_e32 v153, v157, v161
	v_mul_f32_e32 v157, v107, v111
	v_rcp_f32_e32 v157, v157
	v_fmamk_f32 v106, v106, 0xbfb8aa3b, v134
	v_mul_f32_e32 v111, v111, v157
	v_mul_f32_e32 v136, 0xbfb8aa3b, v136
	v_mul_f32_e32 v111, v111, v136
	v_exp_f32_e32 v111, v111
	v_mul_f32_e32 v107, v107, v157
	v_fmamk_f32 v110, v110, 0xbfb8aa3b, v135
	v_exp_f32_e32 v106, v106
	v_fma_f32 v157, -v111, v111, 1.0
	v_max_f32_e32 v157, 0, v157
	v_exp_f32_e32 v110, v110
	v_sqrt_f32_e32 v157, v157
	v_lshlrev_b32_e32 v162, 16, v162
	v_fmac_f32_e32 v153, v158, v162
	v_mul_f32_e32 v107, v107, v153
	v_add_f32_e32 v106, 1.0, v106
	v_add_f32_e32 v110, 1.0, v110
	v_mul_f32_e32 v107, v157, v107
	v_mul_f32_e32 v157, v106, v110
	v_rcp_f32_e32 v157, v157
	v_fmamk_f32 v105, v105, 0xbfb8aa3b, v134
	v_mul_f32_e32 v110, v110, v157
	v_mul_f32_e32 v110, v110, v136
	v_exp_f32_e32 v110, v110
	v_mul_f32_e32 v106, v106, v157
	v_fmamk_f32 v109, v109, 0xbfb8aa3b, v135
	v_exp_f32_e32 v105, v105
	v_fma_f32 v157, -v110, v110, 1.0
	v_max_f32_e32 v157, 0, v157
	v_exp_f32_e32 v109, v109
	v_sqrt_f32_e32 v157, v157
	v_fmac_f32_e32 v156, v158, v161
	v_mul_f32_e32 v106, v106, v156
	v_add_f32_e32 v105, 1.0, v105
	v_add_f32_e32 v109, 1.0, v109
	v_mul_f32_e32 v106, v157, v106
	v_mul_f32_e32 v157, v105, v109
	v_rcp_f32_e32 v157, v157
	v_fmamk_f32 v104, v104, 0xbfb8aa3b, v134
	v_mul_f32_e32 v109, v109, v157
	v_mul_f32_e32 v109, v109, v136
	v_mul_f32_e32 v105, v105, v157
	v_exp_f32_e32 v157, v109
	v_fmamk_f32 v108, v108, 0xbfb8aa3b, v135
	v_exp_f32_e32 v104, v104
	v_exp_f32_e32 v108, v108
	v_fma_f32 v109, -v157, v157, 1.0
	v_max_f32_e32 v109, 0, v109
	v_sqrt_f32_e32 v109, v109
	v_fmac_f32_e32 v155, v158, v160
	ds_bpermute_b32 v147, v80, v113 offset:64
	ds_bpermute_b32 v148, v80, v115 offset:64
	v_mfma_f32_16x16x32_bf16 v[80:83], v[0:3], v[16:19], 0
	v_mul_f32_e32 v105, v105, v155
	v_add_f32_e32 v104, 1.0, v104
	v_add_f32_e32 v108, 1.0, v108
	v_mul_f32_e32 v105, v109, v105
	v_mul_f32_e32 v109, v104, v108
	v_rcp_f32_e32 v109, v109
	v_mfma_f32_16x16x32_bf16 v[96:99], v[4:7], v[20:23], v[80:83]
	v_fmac_f32_e32 v154, v158, v159
	v_lshl_add_u64 v[120:121], v[118:119], 0, s[70:71]
	v_mul_f32_e32 v108, v108, v109
	v_mfma_f32_16x16x32_bf16 v[80:83], v[0:3], v[24:27], 0
	v_mul_f32_e32 v108, v108, v136
	v_exp_f32_e32 v158, v108
	v_mfma_f32_16x16x32_bf16 v[100:103], v[4:7], v[28:31], v[80:83]
	s_nop 0
	v_fmamk_f32 v99, v99, 0xbfb8aa3b, v134
	v_fma_f32 v108, -v158, v158, 1.0
	v_max_f32_e32 v108, 0, v108
	v_exp_f32_e32 v99, v99
	s_nop 2
	s_nop 0
	v_fmamk_f32 v103, v103, 0xbfb8aa3b, v135
	v_exp_f32_e32 v103, v103
	v_sqrt_f32_e32 v108, v108
	v_mul_f32_e32 v104, v104, v109
	v_mul_f32_e32 v104, v104, v154
	v_add_f32_e32 v99, 1.0, v99
	v_add_f32_e32 v103, 1.0, v103
	v_mul_f32_e32 v104, v108, v104
	v_mul_f32_e32 v108, v99, v103
	v_rcp_f32_e32 v108, v108
	v_fmamk_f32 v98, v98, 0xbfb8aa3b, v134
	v_mul_f32_e32 v99, v99, v108
	v_mul_f32_e32 v109, v99, v152
	v_mul_f32_e32 v99, v103, v108
	v_mul_f32_e32 v99, v99, v136
	v_fmamk_f32 v102, v102, 0xbfb8aa3b, v135
	v_exp_f32_e32 v98, v98
	v_exp_f32_e32 v102, v102
	v_exp_f32_e32 v99, v99
	v_add_f32_e32 v98, 1.0, v98
	v_add_f32_e32 v102, 1.0, v102
	v_fma_f32 v103, -v99, v99, 1.0
	v_mul_f32_e32 v108, v98, v102
	v_fmamk_f32 v97, v97, 0xbfb8aa3b, v134
	v_fmamk_f32 v101, v101, 0xbfb8aa3b, v135
	v_max_f32_e32 v103, 0, v103
	v_rcp_f32_e32 v108, v108
	v_exp_f32_e32 v97, v97
	v_exp_f32_e32 v101, v101
	v_sqrt_f32_e32 v103, v103
	v_mul_f32_e32 v98, v98, v108
	v_add_f32_e32 v97, 1.0, v97
	v_add_f32_e32 v101, 1.0, v101
	v_mul_f32_e32 v103, v103, v109
	v_mul_f32_e32 v109, v98, v151
	v_mul_f32_e32 v98, v102, v108
	v_mul_f32_e32 v108, v97, v101
	v_rcp_f32_e32 v108, v108
	v_mul_f32_e32 v98, v98, v136
	v_mul_f32_e32 v101, v101, v108
	v_mul_f32_e32 v101, v101, v136
	v_exp_f32_e32 v101, v101
	v_mul_f32_e32 v97, v97, v108
	v_fmamk_f32 v96, v96, 0xbfb8aa3b, v134
	v_fmamk_f32 v100, v100, 0xbfb8aa3b, v135
	v_fma_f32 v108, -v101, v101, 1.0
	v_max_f32_e32 v108, 0, v108
	v_exp_f32_e32 v96, v96
	v_exp_f32_e32 v100, v100
	v_exp_f32_e32 v98, v98
	v_sqrt_f32_e32 v108, v108
	v_mul_f32_e32 v97, v97, v150
	v_add_f32_e32 v96, 1.0, v96
	v_add_f32_e32 v100, 1.0, v100
	v_fma_f32 v102, -v98, v98, 1.0
	v_mul_f32_e32 v97, v108, v97
	v_mul_f32_e32 v108, v96, v100
	v_max_f32_e32 v102, 0, v102
	v_rcp_f32_e32 v108, v108
	v_sqrt_f32_e32 v102, v102
	v_mfma_f32_16x16x32_bf16 v[80:83], v[0:3], v[32:35], 0
	v_mul_f32_e32 v96, v96, v108
	v_mul_f32_e32 v102, v102, v109
	v_mul_f32_e32 v109, v96, v149
	v_mul_f32_e32 v96, v100, v108
	v_mul_f32_e32 v96, v96, v136
	v_exp_f32_e32 v96, v96
	v_mfma_f32_16x16x32_bf16 v[88:91], v[8:11], v[32:35], 0
	v_fma_f32 v100, -v96, v96, 1.0
	v_max_f32_e32 v100, 0, v100
	v_sqrt_f32_e32 v100, v100
	v_mfma_f32_16x16x32_bf16 v[84:87], v[4:7], v[36:39], v[80:83]
	v_mul_f32_e32 v100, v100, v109
	v_fma_f32 v108, 0, v96, v100
	v_fma_f32 v108, v101, v108, v97
	v_mul_f32_e32 v109, v96, v101
	v_fma_f32 v108, v98, v108, v102
	v_mul_f32_e32 v109, v98, v109
	v_fma_f32 v108, v99, v108, v103
	v_mul_f32_e32 v109, v99, v109
	ds_bpermute_b32 v159, v131, v109
	ds_bpermute_b32 v160, v131, v108
	v_mfma_f32_16x16x32_bf16 v[92:95], v[12:15], v[36:39], v[88:91]
	s_waitcnt lgkmcnt(1)
	v_mul_f32_e32 v159, v109, v159
	s_waitcnt lgkmcnt(0)
	v_fma_f32 v160, v109, v160, v108
	v_cndmask_b32_e64 v108, v160, v108, s[44:45]
	v_cndmask_b32_e64 v109, v159, v109, s[44:45]
	ds_bpermute_b32 v159, v129, v109
	ds_bpermute_b32 v160, v129, v108
	v_mfma_f32_16x16x32_bf16 v[80:83], v[0:3], v[40:43], 0
	s_waitcnt lgkmcnt(1)
	v_mul_f32_e32 v159, v109, v159
	s_waitcnt lgkmcnt(0)
	v_fma_f32 v160, v109, v160, v108
	v_cndmask_b32_e64 v160, v108, v160, s[46:47]
	v_cndmask_b32_e64 v108, v109, v159, s[46:47]
	ds_bpermute_b32 v159, v132, v108
	ds_bpermute_b32 v161, v132, v160
	ds_bpermute_b32 v109, v131, v160
	v_mul_f32_e32 v160, v158, v157
	v_mul_f32_e32 v160, v110, v160
	v_mul_f32_e32 v160, v111, v160
	s_waitcnt lgkmcnt(1)
	v_fmac_f32_e32 v161, v147, v159
	v_fma_f32 v159, 0, v158, v104
	v_fma_f32 v159, v157, v159, v105
	v_fma_f32 v159, v110, v159, v106
	v_fma_f32 v159, v111, v159, v107
	ds_bpermute_b32 v162, v131, v160
	ds_bpermute_b32 v163, v131, v159
	v_mfma_f32_16x16x32_bf16 v[88:91], v[8:11], v[40:43], 0
	ds_bpermute_b32 v108, v131, v108
	s_waitcnt lgkmcnt(2)
	v_mul_f32_e32 v162, v160, v162
	s_waitcnt lgkmcnt(1)
	v_fma_f32 v163, v160, v163, v159
	v_cndmask_b32_e64 v159, v163, v159, s[44:45]
	v_cndmask_b32_e64 v160, v162, v160, s[44:45]
	ds_bpermute_b32 v162, v129, v160
	ds_bpermute_b32 v163, v129, v159
	v_mfma_f32_16x16x32_bf16 v[80:83], v[4:7], v[44:47], v[80:83]
	s_waitcnt lgkmcnt(1)
	v_mul_f32_e32 v162, v160, v162
	s_waitcnt lgkmcnt(0)
	v_fma_f32 v163, v160, v163, v159
	v_cndmask_b32_e64 v159, v159, v163, s[46:47]
	v_cndmask_b32_e64 v160, v160, v162, s[46:47]
	ds_bpermute_b32 v160, v131, v160
	ds_bpermute_b32 v159, v131, v159
	v_mfma_f32_16x16x32_bf16 v[88:91], v[12:15], v[44:47], v[88:91]
	s_waitcnt lgkmcnt(1)
	v_cndmask_b32_e64 v160, v160, 1.0, s[44:45]
	s_waitcnt lgkmcnt(0)
	v_cndmask_b32_e64 v159, v159, 0, s[44:45]
	v_fmac_f32_e32 v159, v161, v160
	v_fmac_f32_e32 v104, v158, v159
	v_fmac_f32_e32 v105, v157, v104
	v_fmac_f32_e32 v106, v110, v105
	v_fmac_f32_e32 v107, v111, v106
	s_and_saveexec_b64 s[4:5], s[68:69]
	s_cbranch_execz .LBB0_829
	v_add_co_u32_e32 v110, vcc, 0x6000000, v120
	s_nop 1
	v_addc_co_u32_e32 v111, vcc, 0, v121, vcc
	global_store_dword v[110:111], v107, off offset:64
.LBB0_829:
	s_or_b64 exec, exec, s[4:5]
	v_mul_f32_e32 v137, 0xbfb8aa3b, v137
	v_mul_f32_e32 v138, 0xbfb8aa3b, v138
	v_fmamk_f32 v95, v95, 0xbfb8aa3b, v137
	v_fmamk_f32 v91, v91, 0xbfb8aa3b, v138
	v_exp_f32_e32 v95, v95
	v_exp_f32_e32 v91, v91
	v_add_f32_e32 v95, 1.0, v95
	v_add_f32_e32 v91, 1.0, v91
	v_fmamk_f32 v94, v94, 0xbfb8aa3b, v137
	v_fmamk_f32 v90, v90, 0xbfb8aa3b, v138
	v_mul_f32_e32 v110, v95, v91
	v_exp_f32_e32 v94, v94
	v_exp_f32_e32 v90, v90
	v_rcp_f32_e32 v110, v110
	v_add_f32_e32 v94, 1.0, v94
	v_add_f32_e32 v90, 1.0, v90
	v_fmamk_f32 v93, v93, 0xbfb8aa3b, v137
	v_fmamk_f32 v89, v89, 0xbfb8aa3b, v138
	v_mul_f32_e32 v95, v95, v110
	v_mul_f32_e32 v91, v91, v110
	v_mul_f32_e32 v110, v94, v90
	v_exp_f32_e32 v93, v93
	v_exp_f32_e32 v89, v89
	v_rcp_f32_e32 v110, v110
	v_add_f32_e32 v93, 1.0, v93
	v_add_f32_e32 v89, 1.0, v89
	v_fmamk_f32 v92, v92, 0xbfb8aa3b, v137
	v_fmamk_f32 v88, v88, 0xbfb8aa3b, v138
	v_mul_f32_e32 v94, v94, v110
	v_mul_f32_e32 v90, v90, v110
	v_mul_f32_e32 v110, v93, v89
	v_exp_f32_e32 v92, v92
	v_exp_f32_e32 v88, v88
	v_rcp_f32_e32 v110, v110
	v_add_f32_e32 v92, 1.0, v92
	v_add_f32_e32 v88, 1.0, v88
	v_fmamk_f32 v87, v87, 0xbfb8aa3b, v137
	v_fmamk_f32 v83, v83, 0xbfb8aa3b, v138
	v_mul_f32_e32 v93, v93, v110
	v_mul_f32_e32 v89, v89, v110
	v_mul_f32_e32 v110, v92, v88
	v_exp_f32_e32 v87, v87
	v_exp_f32_e32 v83, v83
	v_rcp_f32_e32 v110, v110
	v_add_f32_e32 v87, 1.0, v87
	v_add_f32_e32 v83, 1.0, v83
	v_mul_f32_e32 v92, v92, v110
	v_mul_f32_e32 v88, v88, v110
	v_mul_f32_e32 v110, v87, v83
	v_rcp_f32_e32 v110, v110
	v_fmamk_f32 v86, v86, 0xbfb8aa3b, v137
	v_fmamk_f32 v82, v82, 0xbfb8aa3b, v138
	v_mul_f32_e32 v83, v83, v110
	v_mul_f32_e32 v139, 0xbfb8aa3b, v139
	v_mul_f32_e32 v83, v83, v139
	v_mul_f32_e32 v87, v87, v110
	v_exp_f32_e32 v110, v83
	v_exp_f32_e32 v86, v86
	v_exp_f32_e32 v82, v82
	v_mul_f32_e32 v87, v87, v152
	v_fma_f32 v83, -v110, v110, 1.0
	v_max_f32_e32 v83, 0, v83
	v_sqrt_f32_e32 v83, v83
	v_add_f32_e32 v86, 1.0, v86
	v_add_f32_e32 v82, 1.0, v82
	v_mul_f32_e32 v91, v91, v139
	v_mul_f32_e32 v83, v87, v83
	v_mul_f32_e32 v87, v86, v82
	v_rcp_f32_e32 v87, v87
	v_mul_f32_e32 v111, v95, v153
	v_exp_f32_e32 v95, v91
	v_mul_f32_e32 v82, v82, v87
	v_mul_f32_e32 v82, v82, v139
	v_fma_f32 v91, -v95, v95, 1.0
	v_mul_f32_e32 v86, v86, v87
	v_exp_f32_e32 v87, v82
	v_max_f32_e32 v91, 0, v91
	v_sqrt_f32_e32 v91, v91
	v_mul_f32_e32 v90, v90, v139
	v_fma_f32 v82, -v87, v87, 1.0
	v_fmamk_f32 v85, v85, 0xbfb8aa3b, v137
	v_fmamk_f32 v81, v81, 0xbfb8aa3b, v138
	v_max_f32_e32 v82, 0, v82
	v_exp_f32_e32 v85, v85
	v_exp_f32_e32 v81, v81
	v_mul_f32_e32 v91, v91, v111
	v_mul_f32_e32 v111, v94, v156
	v_exp_f32_e32 v94, v90
	v_sqrt_f32_e32 v82, v82
	v_mul_f32_e32 v86, v86, v151
	v_add_f32_e32 v85, 1.0, v85
	v_add_f32_e32 v81, 1.0, v81
	v_fma_f32 v90, -v94, v94, 1.0
	v_mul_f32_e32 v82, v86, v82
	v_mul_f32_e32 v86, v85, v81
	v_max_f32_e32 v90, 0, v90
	v_rcp_f32_e32 v86, v86
	v_sqrt_f32_e32 v90, v90
	v_mul_f32_e32 v89, v89, v139
	v_mul_f32_e32 v81, v81, v86
	v_mul_f32_e32 v90, v90, v111
	v_mul_f32_e32 v111, v93, v155
	v_exp_f32_e32 v93, v89
	v_mul_f32_e32 v81, v81, v139
	v_mul_f32_e32 v85, v85, v86
	v_exp_f32_e32 v86, v81
	v_fma_f32 v89, -v93, v93, 1.0
	v_max_f32_e32 v89, 0, v89
	v_sqrt_f32_e32 v89, v89
	v_fma_f32 v81, -v86, v86, 1.0
	v_fmamk_f32 v84, v84, 0xbfb8aa3b, v137
	v_fmamk_f32 v80, v80, 0xbfb8aa3b, v138
	v_max_f32_e32 v81, 0, v81
	v_exp_f32_e32 v84, v84
	v_exp_f32_e32 v80, v80
	v_mul_f32_e32 v88, v88, v139
	v_sqrt_f32_e32 v81, v81
	v_mul_f32_e32 v89, v89, v111
	v_mul_f32_e32 v111, v92, v154
	v_exp_f32_e32 v92, v88
	v_mul_f32_e32 v85, v85, v150
	v_add_f32_e32 v84, 1.0, v84
	v_add_f32_e32 v80, 1.0, v80
	v_mul_f32_e32 v81, v85, v81
	v_mul_f32_e32 v85, v84, v80
	v_rcp_f32_e32 v85, v85
	v_fma_f32 v88, -v92, v92, 1.0
	v_max_f32_e32 v88, 0, v88
	v_sqrt_f32_e32 v88, v88
	v_mul_f32_e32 v80, v80, v85
	v_mul_f32_e32 v80, v80, v139
	v_mul_f32_e32 v88, v88, v111
	v_exp_f32_e32 v111, v80
	v_mul_f32_e32 v84, v84, v85
	v_mul_f32_e32 v84, v84, v149
	v_mul_f32_e32 v85, v95, v94
	v_fma_f32 v80, -v111, v111, 1.0
	v_max_f32_e32 v80, 0, v80
	v_sqrt_f32_e32 v80, v80
	v_mul_f32_e32 v85, v93, v85
	v_mul_f32_e32 v85, v92, v85
	ds_bpermute_b32 v149, v128, v85
	v_mul_f32_e32 v80, v84, v80
	v_fma_f32 v84, 0, v95, v91
	v_fma_f32 v84, v94, v84, v90
	v_fma_f32 v84, v93, v84, v89
	v_fma_f32 v84, v92, v84, v88
	ds_bpermute_b32 v150, v128, v84
	s_waitcnt lgkmcnt(1)
	v_mul_f32_e32 v149, v85, v149
	s_waitcnt lgkmcnt(0)
	v_fma_f32 v150, v85, v150, v84
	v_cndmask_b32_e64 v84, v150, v84, s[40:41]
	v_cndmask_b32_e64 v85, v149, v85, s[40:41]
	ds_bpermute_b32 v149, v129, v85
	ds_bpermute_b32 v150, v129, v84
	s_waitcnt lgkmcnt(1)
	v_mul_f32_e32 v149, v85, v149
	s_waitcnt lgkmcnt(0)
	v_fma_f32 v150, v85, v150, v84
	v_cndmask_b32_e64 v150, v84, v150, s[42:43]
	v_cndmask_b32_e64 v84, v85, v149, s[42:43]
	ds_bpermute_b32 v149, v130, v84
	ds_bpermute_b32 v151, v130, v150
	ds_bpermute_b32 v85, v128, v150
	v_mul_f32_e32 v150, v110, v87
	v_mul_f32_e32 v150, v86, v150
	v_mul_f32_e32 v150, v111, v150
	s_waitcnt lgkmcnt(1)
	v_fmac_f32_e32 v151, v148, v149
	v_fma_f32 v149, 0, v110, v83
	v_fma_f32 v149, v87, v149, v82
	v_fma_f32 v149, v86, v149, v81
	v_fma_f32 v149, v111, v149, v80
	ds_bpermute_b32 v152, v128, v150
	ds_bpermute_b32 v153, v128, v149
	ds_bpermute_b32 v84, v128, v84
	s_waitcnt lgkmcnt(2)
	v_mul_f32_e32 v152, v150, v152
	s_waitcnt lgkmcnt(1)
	v_fma_f32 v153, v150, v153, v149
	v_cndmask_b32_e64 v149, v153, v149, s[40:41]
	v_cndmask_b32_e64 v150, v152, v150, s[40:41]
	ds_bpermute_b32 v152, v129, v150
	ds_bpermute_b32 v153, v129, v149
	s_waitcnt lgkmcnt(1)
	v_mul_f32_e32 v152, v150, v152
	s_waitcnt lgkmcnt(0)
	v_fma_f32 v153, v150, v153, v149
	v_cndmask_b32_e64 v149, v149, v153, s[42:43]
	v_cndmask_b32_e64 v150, v150, v152, s[42:43]
	ds_bpermute_b32 v150, v128, v150
	ds_bpermute_b32 v149, v128, v149
	s_waitcnt lgkmcnt(1)
	v_cndmask_b32_e64 v150, v150, 1.0, s[40:41]
	s_waitcnt lgkmcnt(0)
	v_cndmask_b32_e64 v149, v149, 0, s[40:41]
	v_fmac_f32_e32 v149, v151, v150
	v_fmac_f32_e32 v83, v110, v149
	v_fmac_f32_e32 v82, v87, v83
	v_fmac_f32_e32 v81, v86, v82
	v_fmac_f32_e32 v80, v111, v81
	s_and_saveexec_b64 s[4:5], s[66:67]
	s_cbranch_execz .LBB0_831
	v_add_co_u32_e32 v86, vcc, 0x6000000, v120
	s_nop 1
	v_addc_co_u32_e32 v87, vcc, 0, v121, vcc
	global_store_dword v[86:87], v80, off offset:2112
